# batched loads in ada (w_ada column sums), kmean and compression-MLP loops; dwordx4 residual epilogue stores
# speedup vs baseline: 1.0435x; 1.0217x over previous
; DI void ada_task(const Params& p, int task, char* smem) {
;     ...
;   const float* w = p.in[3] + ((size_t)l * 1024 + kq * 256) * 6144 + n0 + j;
;   float a0 = 0.f, a1 = 0.f;
; #pragma unroll 8
;   for (int k = 0; k < 256; ++k) { const float wv = w[(size_t)k * 6144]; a0 += sc[kq * 256 + k] * wv; a1 += sc[1024 + kq * 256 + k] * wv; }
.LBB0_55:
	v_lshl_add_u64 v[94:95], v[6:7], 0, s[0:1]
	global_load_dword v30, v[94:95], off
	v_add_co_u32_e32 v94, vcc, 0x6000, v94
	s_nop 1
	v_addc_co_u32_e32 v95, vcc, 0, v95, vcc
	global_load_dword v32, v[94:95], off
	v_add_co_u32_e32 v94, vcc, 0x6000, v94
	s_nop 1
	v_addc_co_u32_e32 v95, vcc, 0, v95, vcc
	global_load_dword v34, v[94:95], off
	v_add_co_u32_e32 v94, vcc, 0x6000, v94
	s_nop 1
	v_addc_co_u32_e32 v95, vcc, 0, v95, vcc
	global_load_dword v36, v[94:95], off
	v_add_co_u32_e32 v94, vcc, 0x6000, v94
	s_nop 1
	v_addc_co_u32_e32 v95, vcc, 0, v95, vcc
	global_load_dword v38, v[94:95], off
	v_add_co_u32_e32 v94, vcc, 0x6000, v94
	s_nop 1
	v_addc_co_u32_e32 v95, vcc, 0, v95, vcc
	global_load_dword v40, v[94:95], off
	v_add_co_u32_e32 v94, vcc, 0x6000, v94
	s_nop 1
	v_addc_co_u32_e32 v95, vcc, 0, v95, vcc
	global_load_dword v42, v[94:95], off
	v_add_co_u32_e32 v94, vcc, 0x6000, v94
	s_nop 1
	v_addc_co_u32_e32 v95, vcc, 0, v95, vcc
	global_load_dword v44, v[94:95], off
	v_add_co_u32_e32 v94, vcc, 0x6000, v94
	s_nop 1
	v_addc_co_u32_e32 v95, vcc, 0, v95, vcc
	global_load_dword v46, v[94:95], off
	v_add_co_u32_e32 v94, vcc, 0x6000, v94
	s_nop 1
	v_addc_co_u32_e32 v95, vcc, 0, v95, vcc
	global_load_dword v48, v[94:95], off
	v_add_co_u32_e32 v94, vcc, 0x6000, v94
	s_nop 1
	v_addc_co_u32_e32 v95, vcc, 0, v95, vcc
	global_load_dword v50, v[94:95], off
	v_add_co_u32_e32 v94, vcc, 0x6000, v94
	s_nop 1
	v_addc_co_u32_e32 v95, vcc, 0, v95, vcc
	global_load_dword v52, v[94:95], off
	v_add_co_u32_e32 v94, vcc, 0x6000, v94
	s_nop 1
	v_addc_co_u32_e32 v95, vcc, 0, v95, vcc
	global_load_dword v54, v[94:95], off
	v_add_co_u32_e32 v94, vcc, 0x6000, v94
	s_nop 1
	v_addc_co_u32_e32 v95, vcc, 0, v95, vcc
	global_load_dword v56, v[94:95], off
	v_add_co_u32_e32 v94, vcc, 0x6000, v94
	s_nop 1
	v_addc_co_u32_e32 v95, vcc, 0, v95, vcc
	global_load_dword v58, v[94:95], off
	v_add_co_u32_e32 v94, vcc, 0x6000, v94
	s_nop 1
	v_addc_co_u32_e32 v95, vcc, 0, v95, vcc
	global_load_dword v60, v[94:95], off
	v_add_co_u32_e32 v94, vcc, 0x6000, v94
	s_nop 1
	v_addc_co_u32_e32 v95, vcc, 0, v95, vcc
	global_load_dword v62, v[94:95], off
	v_add_co_u32_e32 v94, vcc, 0x6000, v94
	s_nop 1
	v_addc_co_u32_e32 v95, vcc, 0, v95, vcc
	global_load_dword v64, v[94:95], off
	v_add_co_u32_e32 v94, vcc, 0x6000, v94
	s_nop 1
	v_addc_co_u32_e32 v95, vcc, 0, v95, vcc
	global_load_dword v66, v[94:95], off
	v_add_co_u32_e32 v94, vcc, 0x6000, v94
	s_nop 1
	v_addc_co_u32_e32 v95, vcc, 0, v95, vcc
	global_load_dword v68, v[94:95], off
	v_add_co_u32_e32 v94, vcc, 0x6000, v94
	s_nop 1
	v_addc_co_u32_e32 v95, vcc, 0, v95, vcc
	global_load_dword v70, v[94:95], off
	v_add_co_u32_e32 v94, vcc, 0x6000, v94
	s_nop 1
	v_addc_co_u32_e32 v95, vcc, 0, v95, vcc
	global_load_dword v72, v[94:95], off
	v_add_co_u32_e32 v94, vcc, 0x6000, v94
	s_nop 1
	v_addc_co_u32_e32 v95, vcc, 0, v95, vcc
	global_load_dword v74, v[94:95], off
	v_add_co_u32_e32 v94, vcc, 0x6000, v94
	s_nop 1
	v_addc_co_u32_e32 v95, vcc, 0, v95, vcc
	global_load_dword v76, v[94:95], off
	v_add_co_u32_e32 v94, vcc, 0x6000, v94
	s_nop 1
	v_addc_co_u32_e32 v95, vcc, 0, v95, vcc
	global_load_dword v78, v[94:95], off
	v_add_co_u32_e32 v94, vcc, 0x6000, v94
	s_nop 1
	v_addc_co_u32_e32 v95, vcc, 0, v95, vcc
	global_load_dword v80, v[94:95], off
	v_add_co_u32_e32 v94, vcc, 0x6000, v94
	s_nop 1
	v_addc_co_u32_e32 v95, vcc, 0, v95, vcc
	global_load_dword v82, v[94:95], off
	v_add_co_u32_e32 v94, vcc, 0x6000, v94
	s_nop 1
	v_addc_co_u32_e32 v95, vcc, 0, v95, vcc
	global_load_dword v84, v[94:95], off
	v_add_co_u32_e32 v94, vcc, 0x6000, v94
	s_nop 1
	v_addc_co_u32_e32 v95, vcc, 0, v95, vcc
	global_load_dword v86, v[94:95], off
	v_add_co_u32_e32 v94, vcc, 0x6000, v94
	s_nop 1
	v_addc_co_u32_e32 v95, vcc, 0, v95, vcc
	global_load_dword v88, v[94:95], off
	v_add_co_u32_e32 v94, vcc, 0x6000, v94
	s_nop 1
	v_addc_co_u32_e32 v95, vcc, 0, v95, vcc
	global_load_dword v90, v[94:95], off
	v_add_co_u32_e32 v94, vcc, 0x6000, v94
	s_nop 1
	v_addc_co_u32_e32 v95, vcc, 0, v95, vcc
	global_load_dword v92, v[94:95], off
	ds_read_b128 v[12:15], v0
	ds_read_b128 v[16:19], v0 offset:16
	ds_read_b128 v[20:23], v0 offset:4096
	s_mov_b32 s25, 0x2a000
	s_add_u32 s0, s0, 0x30000
	s_waitcnt lgkmcnt(2)
	v_mov_b32_e32 v28, v12
	s_addc_u32 s1, s1, 0
	s_waitcnt lgkmcnt(0)
	v_mov_b32_e32 v29, v20
	v_mov_b32_e32 v20, v13
	s_cmp_eq_u32 s0, 0x600000
	s_waitcnt vmcnt(31)
	v_pk_fma_f32 v[8:9], v[30:31], v[28:29], v[8:9] op_sel_hi:[0,1,1]
	s_waitcnt vmcnt(30)
	v_pk_fma_f32 v[8:9], v[32:33], v[20:21], v[8:9] op_sel_hi:[0,1,1]
	v_mov_b32_e32 v20, v14
	v_mov_b32_e32 v21, v22
	v_mov_b32_e32 v22, v15
	s_waitcnt vmcnt(29)
	v_pk_fma_f32 v[8:9], v[34:35], v[20:21], v[8:9] op_sel_hi:[0,1,1]
	s_waitcnt vmcnt(28)
	v_pk_fma_f32 v[8:9], v[36:37], v[22:23], v[8:9] op_sel_hi:[0,1,1]
	v_mov_b32_e32 v22, v16
	ds_read_b128 v[12:15], v0 offset:4112
	v_add_u32_e32 v0, 32, v0
	s_waitcnt lgkmcnt(0)
	v_mov_b32_e32 v23, v12
	v_mov_b32_e32 v12, v17
	s_waitcnt vmcnt(27)
	v_pk_fma_f32 v[8:9], v[38:39], v[22:23], v[8:9] op_sel_hi:[0,1,1]
	s_waitcnt vmcnt(26)
	v_pk_fma_f32 v[8:9], v[40:41], v[12:13], v[8:9] op_sel_hi:[0,1,1]
	v_mov_b32_e32 v16, v18
	v_mov_b32_e32 v17, v14
	v_mov_b32_e32 v14, v19
	s_waitcnt vmcnt(25)
	v_pk_fma_f32 v[8:9], v[42:43], v[16:17], v[8:9] op_sel_hi:[0,1,1]
	s_waitcnt vmcnt(24)
	v_pk_fma_f32 v[8:9], v[44:45], v[14:15], v[8:9] op_sel_hi:[0,1,1]
	ds_read_b128 v[12:15], v0
	ds_read_b128 v[16:19], v0 offset:16
	ds_read_b128 v[20:23], v0 offset:4096
	s_mov_b32 s25, 0x2a000
	s_add_u32 s0, s0, 0x30000
	s_waitcnt lgkmcnt(2)
; DI void ada_task(const Params& p, int task, char* smem) {
;     ...
;   for (int k = 0; k < 256; ++k) { const float wv = w[(size_t)k * 6144]; a0 += sc[kq * 256 + k] * wv; a1 += sc[1024 + kq * 256 + k] * wv; }
;   red[(kq * 2 + 0) * 64 + j] = a0; red[(kq * 2 + 1) * 64 + j] = a1;
;   __syncthreads();
;   if (tid < 128) {
;     const int b = tid >> 6;
;     float s = red[(0 * 2 + b) * 64 + j] + red[(1 * 2 + b) * 64 + j] + red[(2 * 2 + b) * 64 + j] + red[(3 * 2 + b) * 64 + j];
;     ((float*)(p.ws + O_ADA))[((size_t)l * 2 + b) * 6144 + n0 + j] = s + p.in[4][(size_t)l * 6144 + n0 + j];
;   }
	v_mov_b32_e32 v28, v12
	s_addc_u32 s1, s1, 0
	s_waitcnt lgkmcnt(0)
	v_mov_b32_e32 v29, v20
	v_mov_b32_e32 v20, v13
	s_cmp_eq_u32 s0, 0x600000
	s_waitcnt vmcnt(23)
	v_pk_fma_f32 v[8:9], v[46:47], v[28:29], v[8:9] op_sel_hi:[0,1,1]
	s_waitcnt vmcnt(22)
	v_pk_fma_f32 v[8:9], v[48:49], v[20:21], v[8:9] op_sel_hi:[0,1,1]
	v_mov_b32_e32 v20, v14
	v_mov_b32_e32 v21, v22
	v_mov_b32_e32 v22, v15
	s_waitcnt vmcnt(21)
	v_pk_fma_f32 v[8:9], v[50:51], v[20:21], v[8:9] op_sel_hi:[0,1,1]
	s_waitcnt vmcnt(20)
	v_pk_fma_f32 v[8:9], v[52:53], v[22:23], v[8:9] op_sel_hi:[0,1,1]
	v_mov_b32_e32 v22, v16
	ds_read_b128 v[12:15], v0 offset:4112
	v_add_u32_e32 v0, 32, v0
	s_waitcnt lgkmcnt(0)
	v_mov_b32_e32 v23, v12
	v_mov_b32_e32 v12, v17
	s_waitcnt vmcnt(19)
	v_pk_fma_f32 v[8:9], v[54:55], v[22:23], v[8:9] op_sel_hi:[0,1,1]
	s_waitcnt vmcnt(18)
	v_pk_fma_f32 v[8:9], v[56:57], v[12:13], v[8:9] op_sel_hi:[0,1,1]
	v_mov_b32_e32 v16, v18
	v_mov_b32_e32 v17, v14
	v_mov_b32_e32 v14, v19
	s_waitcnt vmcnt(17)
	v_pk_fma_f32 v[8:9], v[58:59], v[16:17], v[8:9] op_sel_hi:[0,1,1]
	s_waitcnt vmcnt(16)
	v_pk_fma_f32 v[8:9], v[60:61], v[14:15], v[8:9] op_sel_hi:[0,1,1]
	ds_read_b128 v[12:15], v0
	ds_read_b128 v[16:19], v0 offset:16
	ds_read_b128 v[20:23], v0 offset:4096
	s_mov_b32 s25, 0x2a000
	s_add_u32 s0, s0, 0x30000
	s_waitcnt lgkmcnt(2)
	v_mov_b32_e32 v28, v12
	s_addc_u32 s1, s1, 0
	s_waitcnt lgkmcnt(0)
	v_mov_b32_e32 v29, v20
	v_mov_b32_e32 v20, v13
	s_cmp_eq_u32 s0, 0x600000
	s_waitcnt vmcnt(15)
	v_pk_fma_f32 v[8:9], v[62:63], v[28:29], v[8:9] op_sel_hi:[0,1,1]
	s_waitcnt vmcnt(14)
	v_pk_fma_f32 v[8:9], v[64:65], v[20:21], v[8:9] op_sel_hi:[0,1,1]
	v_mov_b32_e32 v20, v14
	v_mov_b32_e32 v21, v22
	v_mov_b32_e32 v22, v15
	s_waitcnt vmcnt(13)
	v_pk_fma_f32 v[8:9], v[66:67], v[20:21], v[8:9] op_sel_hi:[0,1,1]
	s_waitcnt vmcnt(12)
	v_pk_fma_f32 v[8:9], v[68:69], v[22:23], v[8:9] op_sel_hi:[0,1,1]
	v_mov_b32_e32 v22, v16
	ds_read_b128 v[12:15], v0 offset:4112
	v_add_u32_e32 v0, 32, v0
	s_waitcnt lgkmcnt(0)
	v_mov_b32_e32 v23, v12
	v_mov_b32_e32 v12, v17
	s_waitcnt vmcnt(11)
	v_pk_fma_f32 v[8:9], v[70:71], v[22:23], v[8:9] op_sel_hi:[0,1,1]
	s_waitcnt vmcnt(10)
	v_pk_fma_f32 v[8:9], v[72:73], v[12:13], v[8:9] op_sel_hi:[0,1,1]
	v_mov_b32_e32 v16, v18
	v_mov_b32_e32 v17, v14
	v_mov_b32_e32 v14, v19
	s_waitcnt vmcnt(9)
	v_pk_fma_f32 v[8:9], v[74:75], v[16:17], v[8:9] op_sel_hi:[0,1,1]
	s_waitcnt vmcnt(8)
	v_pk_fma_f32 v[8:9], v[76:77], v[14:15], v[8:9] op_sel_hi:[0,1,1]
	ds_read_b128 v[12:15], v0
	ds_read_b128 v[16:19], v0 offset:16
	ds_read_b128 v[20:23], v0 offset:4096
	s_mov_b32 s25, 0x2a000
	s_add_u32 s0, s0, 0x30000
	s_waitcnt lgkmcnt(2)
	v_mov_b32_e32 v28, v12
	s_addc_u32 s1, s1, 0
	s_waitcnt lgkmcnt(0)
	v_mov_b32_e32 v29, v20
	v_mov_b32_e32 v20, v13
	s_cmp_eq_u32 s0, 0x600000
	s_waitcnt vmcnt(7)
	v_pk_fma_f32 v[8:9], v[78:79], v[28:29], v[8:9] op_sel_hi:[0,1,1]
	s_waitcnt vmcnt(6)
	v_pk_fma_f32 v[8:9], v[80:81], v[20:21], v[8:9] op_sel_hi:[0,1,1]
	v_mov_b32_e32 v20, v14
	v_mov_b32_e32 v21, v22
	v_mov_b32_e32 v22, v15
	s_waitcnt vmcnt(5)
	v_pk_fma_f32 v[8:9], v[82:83], v[20:21], v[8:9] op_sel_hi:[0,1,1]
	s_waitcnt vmcnt(4)
	v_pk_fma_f32 v[8:9], v[84:85], v[22:23], v[8:9] op_sel_hi:[0,1,1]
	v_mov_b32_e32 v22, v16
	ds_read_b128 v[12:15], v0 offset:4112
	v_add_u32_e32 v0, 32, v0
	s_waitcnt lgkmcnt(0)
	v_mov_b32_e32 v23, v12
	v_mov_b32_e32 v12, v17
	s_waitcnt vmcnt(3)
	v_pk_fma_f32 v[8:9], v[86:87], v[22:23], v[8:9] op_sel_hi:[0,1,1]
	s_waitcnt vmcnt(2)
	v_pk_fma_f32 v[8:9], v[88:89], v[12:13], v[8:9] op_sel_hi:[0,1,1]
	v_mov_b32_e32 v16, v18
	v_mov_b32_e32 v17, v14
	v_mov_b32_e32 v14, v19
	s_waitcnt vmcnt(1)
	v_pk_fma_f32 v[8:9], v[90:91], v[16:17], v[8:9] op_sel_hi:[0,1,1]
	s_waitcnt vmcnt(0)
	v_pk_fma_f32 v[8:9], v[92:93], v[14:15], v[8:9] op_sel_hi:[0,1,1]
	s_cbranch_scc0 .LBB0_55
	v_lshlrev_b32_e32 v0, 2, v4
	v_lshl_or_b32 v4, v3, 9, v0
	v_cmp_gt_i32_e32 vcc, s31, v2
	ds_write2st64_b32 v4, v8, v9 offset0:32 offset1:33
	s_waitcnt lgkmcnt(0)
	s_barrier
	s_and_saveexec_b64 s[0:1], vcc
	s_cbranch_execz .LBB0_58
	v_and_b32_e32 v2, 0x3fffffc0, v2
	v_lshl_or_b32 v2, v2, 2, v0
	ds_read_b32 v6, v10 offset:8192
	ds_read2st64_b32 v[4:5], v2 offset0:34 offset1:36
	v_readlane_b32 s44, v246, 1
	ds_read_b32 v2, v2 offset:9728
	s_mul_i32 s25, s9, 0x6000
	v_readlane_b32 s52, v246, 9
	v_readlane_b32 s53, v246, 10
	s_add_u32 s25, s52, s25
	s_addc_u32 s26, s53, 0
	s_lshl_b32 s90, s24, 2
	s_waitcnt lgkmcnt(1)
	v_add_f32_e32 v4, v6, v4
	s_add_u32 s24, s25, s90
	v_add_f32_e32 v4, v4, v5
	s_addc_u32 s25, s26, 0
	s_waitcnt lgkmcnt(0)
	v_add_f32_e32 v2, v4, v2
	global_load_dword v4, v0, s[24:25]
	v_readlane_b32 s24, v246, 37
	v_readlane_b32 s25, v246, 38
	v_lshl_add_u32 v5, s9, 1, v3
	s_movk_i32 s9, 0x6000
	v_readlane_b32 s45, v246, 2
	v_readlane_b32 s46, v246, 3
	v_readlane_b32 s47, v246, 4
	v_readlane_b32 s48, v246, 5
	v_readlane_b32 s49, v246, 6
	v_readlane_b32 s50, v246, 7
	v_readlane_b32 s51, v246, 8
	v_readlane_b32 s54, v246, 11
	v_readlane_b32 s55, v246, 12
	v_readlane_b32 s56, v246, 13
	v_readlane_b32 s57, v246, 14
	v_readlane_b32 s58, v246, 15
	v_readlane_b32 s59, v246, 16
	s_waitcnt vmcnt(0)
	v_add_f32_e32 v4, v2, v4
	v_mov_b64_e32 v[2:3], s[24:25]
	v_mad_i64_i32 v[2:3], s[24:25], v5, s9, v[2:3]
	v_lshl_add_u64 v[2:3], v[2:3], 0, s[90:91]
	v_lshl_add_u64 v[2:3], v[2:3], 0, v[0:1]
	global_store_dword v[2:3], v4, off

; DI float bf_lo(unsigned u) { return __uint_as_float(u << 16); }
; DI float bf_hi(unsigned u) { return __uint_as_float(u & 0xffff0000u); }
; DI void kmean_task(const Params& p, int task, char* smem) {
;     ...
;   const bf16_t* kp = (const bf16_t*)(ws + O_KB) + ((size_t)b * S + blk * 256 + tq * 64) * 512 + cq * 128 + cp * 2;
;   float a0 = 0.f, a1 = 0.f;
; #pragma unroll 8
;   for (int k = 0; k < 64; ++k) { const unsigned u = *(const unsigned*)(kp + (size_t)k * 512); a0 += bf_lo(u); a1 += bf_hi(u); }
.LBB0_535:
	s_mov_b32 s36, 0xbb79000
	v_lshl_add_u64 v[8:9], v[2:3], 0, s[0:1]
	v_add_co_u32_e32 v10, vcc, 0xbb78000, v8
	s_nop 1
	v_addc_co_u32_e32 v11, vcc, 0, v9, vcc
	global_load_dword v14, v[10:11], off
	global_load_dword v15, v[10:11], off offset:1024
	global_load_dword v16, v[10:11], off offset:2048
	global_load_dword v17, v[10:11], off offset:3072
	v_add_co_u32_e32 v10, vcc, 0xbb79000, v8
	s_nop 1
	v_addc_co_u32_e32 v11, vcc, 0, v9, vcc
	global_load_dword v18, v[10:11], off
	global_load_dword v19, v[10:11], off offset:1024
	global_load_dword v20, v[10:11], off offset:2048
	global_load_dword v21, v[10:11], off offset:3072
	s_add_u32 s0, s0, 0x2000
	s_addc_u32 s1, s1, 0
	v_lshl_add_u64 v[8:9], v[2:3], 0, s[0:1]
	v_add_co_u32_e32 v10, vcc, 0xbb78000, v8
	s_nop 1
	v_addc_co_u32_e32 v11, vcc, 0, v9, vcc
	global_load_dword v22, v[10:11], off
	global_load_dword v23, v[10:11], off offset:1024
	global_load_dword v24, v[10:11], off offset:2048
	global_load_dword v25, v[10:11], off offset:3072
	v_add_co_u32_e32 v10, vcc, 0xbb79000, v8
	s_nop 1
	v_addc_co_u32_e32 v11, vcc, 0, v9, vcc
	global_load_dword v26, v[10:11], off
	global_load_dword v27, v[10:11], off offset:1024
	global_load_dword v28, v[10:11], off offset:2048
	global_load_dword v29, v[10:11], off offset:3072
	s_add_u32 s0, s0, 0x2000
	s_addc_u32 s1, s1, 0
	v_lshl_add_u64 v[8:9], v[2:3], 0, s[0:1]
	v_add_co_u32_e32 v10, vcc, 0xbb78000, v8
	s_nop 1
	v_addc_co_u32_e32 v11, vcc, 0, v9, vcc
	global_load_dword v30, v[10:11], off
	global_load_dword v31, v[10:11], off offset:1024
	global_load_dword v32, v[10:11], off offset:2048
	global_load_dword v33, v[10:11], off offset:3072
	v_add_co_u32_e32 v10, vcc, 0xbb79000, v8
	s_nop 1
	v_addc_co_u32_e32 v11, vcc, 0, v9, vcc
	global_load_dword v34, v[10:11], off
	global_load_dword v35, v[10:11], off offset:1024
	global_load_dword v36, v[10:11], off offset:2048
	global_load_dword v37, v[10:11], off offset:3072
	s_add_u32 s0, s0, 0x2000
	s_addc_u32 s1, s1, 0
	v_lshl_add_u64 v[8:9], v[2:3], 0, s[0:1]
	v_add_co_u32_e32 v10, vcc, 0xbb78000, v8
	s_nop 1
	v_addc_co_u32_e32 v11, vcc, 0, v9, vcc
	global_load_dword v38, v[10:11], off
	global_load_dword v39, v[10:11], off offset:1024
	global_load_dword v40, v[10:11], off offset:2048
	global_load_dword v41, v[10:11], off offset:3072
	v_add_co_u32_e32 v10, vcc, 0xbb79000, v8
	s_nop 1
	v_addc_co_u32_e32 v11, vcc, 0, v9, vcc
	global_load_dword v42, v[10:11], off
	global_load_dword v43, v[10:11], off offset:1024
	global_load_dword v44, v[10:11], off offset:2048
	global_load_dword v45, v[10:11], off offset:3072
	s_add_u32 s0, s0, 0x2000
	s_addc_u32 s1, s1, 0
	s_waitcnt vmcnt(31)
	v_lshlrev_b32_e32 v12, 16, v14
	v_and_b32_e32 v13, 0xffff0000, v14
	v_pk_add_f32 v[4:5], v[4:5], v[12:13]
	s_waitcnt vmcnt(30)
	v_lshlrev_b32_e32 v12, 16, v15
	v_and_b32_e32 v13, 0xffff0000, v15
	v_pk_add_f32 v[4:5], v[4:5], v[12:13]
	s_waitcnt vmcnt(29)
	v_lshlrev_b32_e32 v12, 16, v16
	v_and_b32_e32 v13, 0xffff0000, v16
	v_pk_add_f32 v[4:5], v[4:5], v[12:13]
	s_waitcnt vmcnt(28)
	v_lshlrev_b32_e32 v12, 16, v17
	v_and_b32_e32 v13, 0xffff0000, v17
	v_pk_add_f32 v[4:5], v[4:5], v[12:13]
	s_waitcnt vmcnt(27)
	v_lshlrev_b32_e32 v12, 16, v18
	v_and_b32_e32 v13, 0xffff0000, v18
	v_pk_add_f32 v[4:5], v[4:5], v[12:13]
	s_waitcnt vmcnt(26)
	v_lshlrev_b32_e32 v12, 16, v19
	v_and_b32_e32 v13, 0xffff0000, v19
	v_pk_add_f32 v[4:5], v[4:5], v[12:13]
	s_waitcnt vmcnt(25)
	v_lshlrev_b32_e32 v12, 16, v20
	v_and_b32_e32 v13, 0xffff0000, v20
	v_pk_add_f32 v[4:5], v[4:5], v[12:13]
	s_waitcnt vmcnt(24)
	v_lshlrev_b32_e32 v12, 16, v21
	v_and_b32_e32 v13, 0xffff0000, v21
	v_pk_add_f32 v[4:5], v[4:5], v[12:13]
	s_waitcnt vmcnt(23)
	v_lshlrev_b32_e32 v12, 16, v22
	v_and_b32_e32 v13, 0xffff0000, v22
	v_pk_add_f32 v[4:5], v[4:5], v[12:13]
	s_waitcnt vmcnt(22)
	v_lshlrev_b32_e32 v12, 16, v23
	v_and_b32_e32 v13, 0xffff0000, v23
	v_pk_add_f32 v[4:5], v[4:5], v[12:13]
	s_waitcnt vmcnt(21)
	v_lshlrev_b32_e32 v12, 16, v24
	v_and_b32_e32 v13, 0xffff0000, v24
	v_pk_add_f32 v[4:5], v[4:5], v[12:13]
	s_waitcnt vmcnt(20)
	v_lshlrev_b32_e32 v12, 16, v25
	v_and_b32_e32 v13, 0xffff0000, v25
	v_pk_add_f32 v[4:5], v[4:5], v[12:13]
	s_waitcnt vmcnt(19)
	v_lshlrev_b32_e32 v12, 16, v26
	v_and_b32_e32 v13, 0xffff0000, v26
	v_pk_add_f32 v[4:5], v[4:5], v[12:13]
	s_waitcnt vmcnt(18)
	v_lshlrev_b32_e32 v12, 16, v27
	v_and_b32_e32 v13, 0xffff0000, v27
	v_pk_add_f32 v[4:5], v[4:5], v[12:13]
	s_waitcnt vmcnt(17)
	v_lshlrev_b32_e32 v12, 16, v28
	v_and_b32_e32 v13, 0xffff0000, v28
	v_pk_add_f32 v[4:5], v[4:5], v[12:13]
	s_waitcnt vmcnt(16)
	v_lshlrev_b32_e32 v12, 16, v29
	v_and_b32_e32 v13, 0xffff0000, v29
	v_pk_add_f32 v[4:5], v[4:5], v[12:13]
	s_waitcnt vmcnt(15)
	v_lshlrev_b32_e32 v12, 16, v30
	v_and_b32_e32 v13, 0xffff0000, v30
	v_pk_add_f32 v[4:5], v[4:5], v[12:13]
	s_waitcnt vmcnt(14)
	v_lshlrev_b32_e32 v12, 16, v31
	v_and_b32_e32 v13, 0xffff0000, v31
	v_pk_add_f32 v[4:5], v[4:5], v[12:13]
	s_waitcnt vmcnt(13)
	v_lshlrev_b32_e32 v12, 16, v32
	v_and_b32_e32 v13, 0xffff0000, v32
	v_pk_add_f32 v[4:5], v[4:5], v[12:13]
	s_waitcnt vmcnt(12)
	v_lshlrev_b32_e32 v12, 16, v33
	v_and_b32_e32 v13, 0xffff0000, v33
	v_pk_add_f32 v[4:5], v[4:5], v[12:13]
	s_waitcnt vmcnt(11)
	v_lshlrev_b32_e32 v12, 16, v34
	v_and_b32_e32 v13, 0xffff0000, v34
	v_pk_add_f32 v[4:5], v[4:5], v[12:13]
	s_waitcnt vmcnt(10)
	v_lshlrev_b32_e32 v12, 16, v35
	v_and_b32_e32 v13, 0xffff0000, v35
	v_pk_add_f32 v[4:5], v[4:5], v[12:13]
	s_waitcnt vmcnt(9)
	v_lshlrev_b32_e32 v12, 16, v36
	v_and_b32_e32 v13, 0xffff0000, v36
	v_pk_add_f32 v[4:5], v[4:5], v[12:13]
	s_waitcnt vmcnt(8)
	v_lshlrev_b32_e32 v12, 16, v37
	v_and_b32_e32 v13, 0xffff0000, v37
	v_pk_add_f32 v[4:5], v[4:5], v[12:13]
	s_waitcnt vmcnt(7)
	v_lshlrev_b32_e32 v12, 16, v38
	v_and_b32_e32 v13, 0xffff0000, v38
	v_pk_add_f32 v[4:5], v[4:5], v[12:13]
	s_waitcnt vmcnt(6)
	v_lshlrev_b32_e32 v12, 16, v39
	v_and_b32_e32 v13, 0xffff0000, v39
	v_pk_add_f32 v[4:5], v[4:5], v[12:13]
	s_waitcnt vmcnt(5)
	v_lshlrev_b32_e32 v12, 16, v40
	v_and_b32_e32 v13, 0xffff0000, v40
	v_pk_add_f32 v[4:5], v[4:5], v[12:13]
	s_waitcnt vmcnt(4)
	v_lshlrev_b32_e32 v12, 16, v41
	v_and_b32_e32 v13, 0xffff0000, v41
	v_pk_add_f32 v[4:5], v[4:5], v[12:13]
	s_waitcnt vmcnt(3)
	v_lshlrev_b32_e32 v12, 16, v42
	v_and_b32_e32 v13, 0xffff0000, v42
	v_pk_add_f32 v[4:5], v[4:5], v[12:13]
	s_waitcnt vmcnt(2)
	v_lshlrev_b32_e32 v12, 16, v43
	v_and_b32_e32 v13, 0xffff0000, v43
	v_pk_add_f32 v[4:5], v[4:5], v[12:13]
	s_waitcnt vmcnt(1)
	v_lshlrev_b32_e32 v12, 16, v44
	v_and_b32_e32 v13, 0xffff0000, v44
	v_pk_add_f32 v[4:5], v[4:5], v[12:13]
	s_waitcnt vmcnt(0)
	v_lshlrev_b32_e32 v12, 16, v45
	v_and_b32_e32 v13, 0xffff0000, v45
	v_pk_add_f32 v[4:5], v[4:5], v[12:13]
	s_cmp_eq_u32 s0, 0x10000
	s_cbranch_scc0 .LBB0_535
; DI unsigned pk2(float a, float b) { f32x2 v = {a, b}; bf2_t r = __builtin_convertvector(v, bf2_t); return __builtin_bit_cast(unsigned, r); }
; DI void kmean_task(const Params& p, int task, char* smem) {
;     ...
;   red[tq * 128 + cp * 2] = a0; red[tq * 128 + cp * 2 + 1] = a1;
;   __syncthreads();
;   if (tid < 128) {
;     const float s = (red[tid] + red[128 + tid] + red[256 + tid] + red[384 + tid]) * (1.f / 256.f);
;     const int col = cq * 128 + tid, h = col >> 6, d = col & 63;
;     ((bf16_t*)(ws + O_KMEAN))[((size_t)(b * 8 + h) * 32 + blk) * 64 + d] = (bf16_t)(pk2(s, 0.f) & 0xffff);
;   }
;   __syncthreads();
	v_lshlrev_b32_e32 v2, 3, v6
	v_cmp_gt_i32_e32 vcc, s31, v6
	ds_write_b64 v2, v[4:5]
	s_waitcnt lgkmcnt(0)
	s_barrier
	s_and_saveexec_b64 s[0:1], vcc
	s_cbranch_execz .LBB0_538
	v_lshlrev_b32_e32 v4, 2, v6
	ds_read2st64_b32 v[2:3], v4 offset1:2
	s_add_i32 s36, s47, 0xffffff80
	s_lshl_b32 s37, s36, 7
	s_and_b32 s37, s37, 0x180
	s_lshr_b32 s36, s36, 4
	s_waitcnt lgkmcnt(0)
	v_add_f32_e32 v5, v2, v3
	ds_read2st64_b32 v[2:3], v4 offset0:4 offset1:6
	s_and_b32 s36, s36, 0xffffff8
	v_lshlrev_b32_e32 v0, 1, v0
	s_waitcnt lgkmcnt(0)
	v_add_f32_e32 v2, v5, v2
	v_add_f32_e32 v2, v2, v3
	v_add_u32_e32 v3, s37, v6
	v_mul_f32_e32 v2, 0x3b800000, v2
	v_ashrrev_i32_e32 v3, 6, v3
	v_cvt_pk_bf16_f32 v4, v2, s0
	v_add_u32_e32 v2, s36, v3
	v_ashrrev_i32_e32 v3, 31, v2
	v_readlane_b32 s36, v244, 30
	v_lshlrev_b64 v[2:3], 12, v[2:3]
	v_readlane_b32 s37, v244, 31
	s_nop 1
	v_lshl_add_u64 v[2:3], s[36:37], 0, v[2:3]
	s_lshl_b32 s36, s47, 5
	s_and_b32 s90, s36, 0xf80
	v_lshl_add_u64 v[2:3], v[2:3], 0, s[90:91]
	v_lshl_add_u64 v[2:3], v[2:3], 0, v[0:1]
	global_store_short v[2:3], v4, off

; #define MFMA32(a, b, c) __builtin_amdgcn_mfma_f32_32x32x16_bf16((a), (b), (c), 0, 0, 0)
; DI unsigned pk2(float a, float b) { f32x2 v = {a, b}; bf2_t r = __builtin_convertvector(v, bf2_t); return __builtin_bit_cast(unsigned, r); }
; DI float bf_lo(unsigned u) { return __uint_as_float(u << 16); }
; DI float bf_hi(unsigned u) { return __uint_as_float(u & 0xffff0000u); }
; DI void cmp_tile(const Params& p, int l, int tile, char* smem) {
;     ...
;   const bf16_t* brow = W1T + (size_t)r * 2048 + half * 8;
; #pragma unroll 2
;   for (int t8 = 0; t8 < 8; ++t8) {
;     const int tl = 8 * w + t8;
; #pragma unroll
;     for (int dk = 0; dk < 4; ++dk) {
;       const uint4 av = *(const uint4*)(arow + (size_t)tl * 128 + dk * 16);
;       const float4 p0 = *(const float4*)(pe + tl * 64 + dk * 16 + half * 8);
;       const float4 p1 = *(const float4*)(pe + tl * 64 + dk * 16 + half * 8 + 4);
;       uint4 a2;
;       a2.x = pk2(bf_lo(av.x) + p0.x, bf_hi(av.x) + p0.y);
;       a2.y = pk2(bf_lo(av.y) + p0.z, bf_hi(av.y) + p0.w);
;       a2.z = pk2(bf_lo(av.z) + p1.x, bf_hi(av.z) + p1.y);
;       a2.w = pk2(bf_lo(av.w) + p1.z, bf_hi(av.w) + p1.w);
;       const bf16x8 a8 = __builtin_bit_cast(bf16x8, a2);
; #pragma unroll
;       for (int nf = 0; nf < 4; ++nf) {
;         const bf16x8 bv = *(const bf16x8*)(brow + (size_t)(nf * 32) * 2048 + tl * 64 + dk * 16);
;         acc[nf] = MFMA32(a8, bv, acc[nf]);
;       }
;     }
;   }
.LBB0_541:
	v_lshl_add_u64 v[68:69], v[76:77], 0, v[0:1]
	v_lshl_add_u64 v[66:67], v[74:75], 0, s[42:43]
	v_lshl_add_u64 v[84:85], v[72:73], 0, v[0:1]
	v_add_co_u32_e32 v82, vcc, s35, v84
	s_nop 1
	v_addc_co_u32_e32 v83, vcc, 0, v85, vcc
	v_add_co_u32_e32 v78, vcc, s41, v84
	s_nop 1
	v_addc_co_u32_e32 v79, vcc, 0, v85, vcc
	v_add_co_u32_e32 v80, vcc, s15, v84
	s_nop 1
	v_addc_co_u32_e32 v81, vcc, 0, v85, vcc
	global_load_dwordx4 v[104:107], v[68:69], off
	global_load_dwordx4 v[108:111], v[66:67], off
	global_load_dwordx4 v[112:115], v[66:67], off offset:16
	global_load_dwordx4 v[116:119], v[84:85], off
	global_load_dwordx4 v[120:123], v[82:83], off
	global_load_dwordx4 v[124:127], v[78:79], off
	global_load_dwordx4 v[128:131], v[80:81], off
	global_load_dwordx4 v[132:135], v[68:69], off offset:32
	global_load_dwordx4 v[136:139], v[66:67], off offset:64
	global_load_dwordx4 v[140:143], v[66:67], off offset:80
	global_load_dwordx4 v[144:147], v[84:85], off offset:32
	global_load_dwordx4 v[148:151], v[82:83], off offset:32
	global_load_dwordx4 v[152:155], v[78:79], off offset:32
	global_load_dwordx4 v[156:159], v[80:81], off offset:32
	s_waitcnt vmcnt(11)
	v_lshlrev_b32_e32 v164, 16, v104
	v_and_b32_e32 v165, 0xffff0000, v104
	v_pk_add_f32 v[164:165], v[108:109], v[164:165]
	v_cvt_pk_bf16_f32 v160, v164, v165
	v_lshlrev_b32_e32 v164, 16, v105
	v_and_b32_e32 v165, 0xffff0000, v105
	v_pk_add_f32 v[164:165], v[110:111], v[164:165]
	v_cvt_pk_bf16_f32 v161, v164, v165
	v_lshlrev_b32_e32 v164, 16, v106
	v_and_b32_e32 v165, 0xffff0000, v106
	v_pk_add_f32 v[164:165], v[112:113], v[164:165]
	v_cvt_pk_bf16_f32 v162, v164, v165
	v_lshlrev_b32_e32 v164, 16, v107
	v_and_b32_e32 v165, 0xffff0000, v107
	v_pk_add_f32 v[164:165], v[114:115], v[164:165]
	v_cvt_pk_bf16_f32 v163, v164, v165
	s_waitcnt vmcnt(10)
	s_nop 1
	v_mfma_f32_32x32x16_bf16 v[2:17], v[160:163], v[116:119], v[2:17]
	s_waitcnt vmcnt(9)
	v_mfma_f32_32x32x16_bf16 v[18:33], v[160:163], v[120:123], v[18:33]
	s_waitcnt vmcnt(8)
	v_mfma_f32_32x32x16_bf16 v[34:49], v[160:163], v[124:127], v[34:49]
	s_waitcnt vmcnt(7)
	v_mfma_f32_32x32x16_bf16 v[50:65], v[160:163], v[128:131], v[50:65]
	global_load_dwordx4 v[104:107], v[68:69], off offset:64
	global_load_dwordx4 v[108:111], v[66:67], off offset:128
	global_load_dwordx4 v[112:115], v[66:67], off offset:144
	global_load_dwordx4 v[116:119], v[84:85], off offset:64
	global_load_dwordx4 v[120:123], v[82:83], off offset:64
	global_load_dwordx4 v[124:127], v[78:79], off offset:64
	global_load_dwordx4 v[128:131], v[80:81], off offset:64
	s_waitcnt vmcnt(11)
	v_lshlrev_b32_e32 v164, 16, v132
	v_and_b32_e32 v165, 0xffff0000, v132
	v_pk_add_f32 v[164:165], v[136:137], v[164:165]
	v_cvt_pk_bf16_f32 v160, v164, v165
	v_lshlrev_b32_e32 v164, 16, v133
	v_and_b32_e32 v165, 0xffff0000, v133
	v_pk_add_f32 v[164:165], v[138:139], v[164:165]
	v_cvt_pk_bf16_f32 v161, v164, v165
	v_lshlrev_b32_e32 v164, 16, v134
	v_and_b32_e32 v165, 0xffff0000, v134
	v_pk_add_f32 v[164:165], v[140:141], v[164:165]
	v_cvt_pk_bf16_f32 v162, v164, v165
	v_lshlrev_b32_e32 v164, 16, v135
	v_and_b32_e32 v165, 0xffff0000, v135
	v_pk_add_f32 v[164:165], v[142:143], v[164:165]
	v_cvt_pk_bf16_f32 v163, v164, v165
	s_waitcnt vmcnt(10)
	s_nop 1
	v_mfma_f32_32x32x16_bf16 v[2:17], v[160:163], v[144:147], v[2:17]
	s_waitcnt vmcnt(9)
	v_mfma_f32_32x32x16_bf16 v[18:33], v[160:163], v[148:151], v[18:33]
	s_waitcnt vmcnt(8)
	v_mfma_f32_32x32x16_bf16 v[34:49], v[160:163], v[152:155], v[34:49]
	s_waitcnt vmcnt(7)
	v_mfma_f32_32x32x16_bf16 v[50:65], v[160:163], v[156:159], v[50:65]
	global_load_dwordx4 v[132:135], v[68:69], off offset:96
	global_load_dwordx4 v[136:139], v[66:67], off offset:192
	global_load_dwordx4 v[140:143], v[66:67], off offset:208
	global_load_dwordx4 v[144:147], v[84:85], off offset:96
	global_load_dwordx4 v[148:151], v[82:83], off offset:96
	global_load_dwordx4 v[152:155], v[78:79], off offset:96
	global_load_dwordx4 v[156:159], v[80:81], off offset:96
	s_waitcnt vmcnt(11)
	v_lshlrev_b32_e32 v164, 16, v104
	v_and_b32_e32 v165, 0xffff0000, v104
	v_pk_add_f32 v[164:165], v[108:109], v[164:165]
	v_cvt_pk_bf16_f32 v160, v164, v165
	v_lshlrev_b32_e32 v164, 16, v105
	v_and_b32_e32 v165, 0xffff0000, v105
	v_pk_add_f32 v[164:165], v[110:111], v[164:165]
	v_cvt_pk_bf16_f32 v161, v164, v165
	v_lshlrev_b32_e32 v164, 16, v106
	v_and_b32_e32 v165, 0xffff0000, v106
	v_pk_add_f32 v[164:165], v[112:113], v[164:165]
	v_cvt_pk_bf16_f32 v162, v164, v165
	v_lshlrev_b32_e32 v164, 16, v107
	v_and_b32_e32 v165, 0xffff0000, v107
	v_pk_add_f32 v[164:165], v[114:115], v[164:165]
	v_cvt_pk_bf16_f32 v163, v164, v165
	s_waitcnt vmcnt(10)
	s_nop 1
	v_mfma_f32_32x32x16_bf16 v[2:17], v[160:163], v[116:119], v[2:17]
	s_waitcnt vmcnt(9)
	v_mfma_f32_32x32x16_bf16 v[18:33], v[160:163], v[120:123], v[18:33]
	s_waitcnt vmcnt(8)
	v_mfma_f32_32x32x16_bf16 v[34:49], v[160:163], v[124:127], v[34:49]
	s_waitcnt vmcnt(7)
	v_mfma_f32_32x32x16_bf16 v[50:65], v[160:163], v[128:131], v[50:65]
	global_load_dwordx4 v[104:107], v[68:69], off offset:256
	global_load_dwordx4 v[108:111], v[66:67], off offset:256
	global_load_dwordx4 v[112:115], v[66:67], off offset:272
	global_load_dwordx4 v[116:119], v[84:85], off offset:128
	global_load_dwordx4 v[120:123], v[82:83], off offset:128
	global_load_dwordx4 v[124:127], v[78:79], off offset:128
	global_load_dwordx4 v[128:131], v[80:81], off offset:128
	s_waitcnt vmcnt(11)
; #define MFMA32(a, b, c) __builtin_amdgcn_mfma_f32_32x32x16_bf16((a), (b), (c), 0, 0, 0)
; DI unsigned pk2(float a, float b) { f32x2 v = {a, b}; bf2_t r = __builtin_convertvector(v, bf2_t); return __builtin_bit_cast(unsigned, r); }
; DI float bf_lo(unsigned u) { return __uint_as_float(u << 16); }
; DI float bf_hi(unsigned u) { return __uint_as_float(u & 0xffff0000u); }
; DI void cmp_tile(const Params& p, int l, int tile, char* smem) {
;     ...
;   for (int t8 = 0; t8 < 8; ++t8) {
;     const int tl = 8 * w + t8;
; #pragma unroll
;     for (int dk = 0; dk < 4; ++dk) {
;       const uint4 av = *(const uint4*)(arow + (size_t)tl * 128 + dk * 16);
;       const float4 p0 = *(const float4*)(pe + tl * 64 + dk * 16 + half * 8);
;       const float4 p1 = *(const float4*)(pe + tl * 64 + dk * 16 + half * 8 + 4);
;       uint4 a2;
;       a2.x = pk2(bf_lo(av.x) + p0.x, bf_hi(av.x) + p0.y);
;       a2.y = pk2(bf_lo(av.y) + p0.z, bf_hi(av.y) + p0.w);
;       a2.z = pk2(bf_lo(av.z) + p1.x, bf_hi(av.z) + p1.y);
;       a2.w = pk2(bf_lo(av.w) + p1.z, bf_hi(av.w) + p1.w);
;       const bf16x8 a8 = __builtin_bit_cast(bf16x8, a2);
; #pragma unroll
;       for (int nf = 0; nf < 4; ++nf) {
;         const bf16x8 bv = *(const bf16x8*)(brow + (size_t)(nf * 32) * 2048 + tl * 64 + dk * 16);
;         acc[nf] = MFMA32(a8, bv, acc[nf]);
;       }
;     }
;   }
	v_lshlrev_b32_e32 v164, 16, v132
	v_and_b32_e32 v165, 0xffff0000, v132
	v_pk_add_f32 v[164:165], v[136:137], v[164:165]
	v_cvt_pk_bf16_f32 v160, v164, v165
	v_lshlrev_b32_e32 v164, 16, v133
	v_and_b32_e32 v165, 0xffff0000, v133
	v_pk_add_f32 v[164:165], v[138:139], v[164:165]
	v_cvt_pk_bf16_f32 v161, v164, v165
	v_lshlrev_b32_e32 v164, 16, v134
	v_and_b32_e32 v165, 0xffff0000, v134
	v_pk_add_f32 v[164:165], v[140:141], v[164:165]
	v_cvt_pk_bf16_f32 v162, v164, v165
	v_lshlrev_b32_e32 v164, 16, v135
	v_and_b32_e32 v165, 0xffff0000, v135
	v_pk_add_f32 v[164:165], v[142:143], v[164:165]
	v_cvt_pk_bf16_f32 v163, v164, v165
	s_waitcnt vmcnt(10)
	s_nop 1
	v_mfma_f32_32x32x16_bf16 v[2:17], v[160:163], v[144:147], v[2:17]
	s_waitcnt vmcnt(9)
	v_mfma_f32_32x32x16_bf16 v[18:33], v[160:163], v[148:151], v[18:33]
	s_waitcnt vmcnt(8)
	v_mfma_f32_32x32x16_bf16 v[34:49], v[160:163], v[152:155], v[34:49]
	s_waitcnt vmcnt(7)
	v_mfma_f32_32x32x16_bf16 v[50:65], v[160:163], v[156:159], v[50:65]
	global_load_dwordx4 v[132:135], v[68:69], off offset:288
	global_load_dwordx4 v[136:139], v[66:67], off offset:320
	global_load_dwordx4 v[140:143], v[66:67], off offset:336
	global_load_dwordx4 v[144:147], v[84:85], off offset:160
	global_load_dwordx4 v[148:151], v[82:83], off offset:160
	global_load_dwordx4 v[152:155], v[78:79], off offset:160
	global_load_dwordx4 v[156:159], v[80:81], off offset:160
	s_waitcnt vmcnt(11)
	v_lshlrev_b32_e32 v164, 16, v104
	v_and_b32_e32 v165, 0xffff0000, v104
	v_pk_add_f32 v[164:165], v[108:109], v[164:165]
	v_cvt_pk_bf16_f32 v160, v164, v165
	v_lshlrev_b32_e32 v164, 16, v105
	v_and_b32_e32 v165, 0xffff0000, v105
	v_pk_add_f32 v[164:165], v[110:111], v[164:165]
	v_cvt_pk_bf16_f32 v161, v164, v165
	v_lshlrev_b32_e32 v164, 16, v106
	v_and_b32_e32 v165, 0xffff0000, v106
	v_pk_add_f32 v[164:165], v[112:113], v[164:165]
	v_cvt_pk_bf16_f32 v162, v164, v165
	v_lshlrev_b32_e32 v164, 16, v107
	v_and_b32_e32 v165, 0xffff0000, v107
	v_pk_add_f32 v[164:165], v[114:115], v[164:165]
	v_cvt_pk_bf16_f32 v163, v164, v165
	s_waitcnt vmcnt(10)
	s_nop 1
	v_mfma_f32_32x32x16_bf16 v[2:17], v[160:163], v[116:119], v[2:17]
	s_waitcnt vmcnt(9)
	v_mfma_f32_32x32x16_bf16 v[18:33], v[160:163], v[120:123], v[18:33]
	s_waitcnt vmcnt(8)
	v_mfma_f32_32x32x16_bf16 v[34:49], v[160:163], v[124:127], v[34:49]
	s_waitcnt vmcnt(7)
	v_mfma_f32_32x32x16_bf16 v[50:65], v[160:163], v[128:131], v[50:65]
	global_load_dwordx4 v[104:107], v[68:69], off offset:320
	global_load_dwordx4 v[108:111], v[66:67], off offset:384
	global_load_dwordx4 v[112:115], v[66:67], off offset:400
	global_load_dwordx4 v[116:119], v[84:85], off offset:192
	global_load_dwordx4 v[120:123], v[82:83], off offset:192
	global_load_dwordx4 v[124:127], v[78:79], off offset:192
	global_load_dwordx4 v[128:131], v[80:81], off offset:192
	s_waitcnt vmcnt(11)
	v_lshlrev_b32_e32 v164, 16, v132
	v_and_b32_e32 v165, 0xffff0000, v132
	v_pk_add_f32 v[164:165], v[136:137], v[164:165]
	v_cvt_pk_bf16_f32 v160, v164, v165
	v_lshlrev_b32_e32 v164, 16, v133
	v_and_b32_e32 v165, 0xffff0000, v133
	v_pk_add_f32 v[164:165], v[138:139], v[164:165]
	v_cvt_pk_bf16_f32 v161, v164, v165
	v_lshlrev_b32_e32 v164, 16, v134
	v_and_b32_e32 v165, 0xffff0000, v134
	v_pk_add_f32 v[164:165], v[140:141], v[164:165]
	v_cvt_pk_bf16_f32 v162, v164, v165
	v_lshlrev_b32_e32 v164, 16, v135
	v_and_b32_e32 v165, 0xffff0000, v135
	v_pk_add_f32 v[164:165], v[142:143], v[164:165]
	v_cvt_pk_bf16_f32 v163, v164, v165
	s_waitcnt vmcnt(10)
	s_nop 1
	v_mfma_f32_32x32x16_bf16 v[2:17], v[160:163], v[144:147], v[2:17]
	s_waitcnt vmcnt(9)
	v_mfma_f32_32x32x16_bf16 v[18:33], v[160:163], v[148:151], v[18:33]
	s_waitcnt vmcnt(8)
	v_mfma_f32_32x32x16_bf16 v[34:49], v[160:163], v[152:155], v[34:49]
	s_waitcnt vmcnt(7)
	v_mfma_f32_32x32x16_bf16 v[50:65], v[160:163], v[156:159], v[50:65]
	global_load_dwordx4 v[132:135], v[68:69], off offset:352
	global_load_dwordx4 v[136:139], v[66:67], off offset:448
	global_load_dwordx4 v[140:143], v[66:67], off offset:464
	global_load_dwordx4 v[144:147], v[84:85], off offset:224
	global_load_dwordx4 v[148:151], v[82:83], off offset:224
	global_load_dwordx4 v[152:155], v[78:79], off offset:224
	global_load_dwordx4 v[156:159], v[80:81], off offset:224
	s_waitcnt vmcnt(11)
	v_lshlrev_b32_e32 v164, 16, v104
	v_and_b32_e32 v165, 0xffff0000, v104
	v_pk_add_f32 v[164:165], v[108:109], v[164:165]
	v_cvt_pk_bf16_f32 v160, v164, v165
	v_lshlrev_b32_e32 v164, 16, v105
	v_and_b32_e32 v165, 0xffff0000, v105
	v_pk_add_f32 v[164:165], v[110:111], v[164:165]
	v_cvt_pk_bf16_f32 v161, v164, v165
	v_lshlrev_b32_e32 v164, 16, v106
	v_and_b32_e32 v165, 0xffff0000, v106
	v_pk_add_f32 v[164:165], v[112:113], v[164:165]
	v_cvt_pk_bf16_f32 v162, v164, v165
	v_lshlrev_b32_e32 v164, 16, v107
	v_and_b32_e32 v165, 0xffff0000, v107
	v_pk_add_f32 v[164:165], v[114:115], v[164:165]
	v_cvt_pk_bf16_f32 v163, v164, v165
	s_waitcnt vmcnt(10)
	s_nop 1
	v_mfma_f32_32x32x16_bf16 v[2:17], v[160:163], v[116:119], v[2:17]
	s_waitcnt vmcnt(9)
	v_mfma_f32_32x32x16_bf16 v[18:33], v[160:163], v[120:123], v[18:33]
	s_waitcnt vmcnt(8)
	v_mfma_f32_32x32x16_bf16 v[34:49], v[160:163], v[124:127], v[34:49]
	s_waitcnt vmcnt(7)
	v_mfma_f32_32x32x16_bf16 v[50:65], v[160:163], v[128:131], v[50:65]
	s_waitcnt vmcnt(4)
	v_lshlrev_b32_e32 v164, 16, v132
	v_and_b32_e32 v165, 0xffff0000, v132
	v_pk_add_f32 v[164:165], v[136:137], v[164:165]
	v_cvt_pk_bf16_f32 v160, v164, v165
	v_lshlrev_b32_e32 v164, 16, v133
	v_and_b32_e32 v165, 0xffff0000, v133
	v_pk_add_f32 v[164:165], v[138:139], v[164:165]
	v_cvt_pk_bf16_f32 v161, v164, v165
	v_lshlrev_b32_e32 v164, 16, v134
	v_and_b32_e32 v165, 0xffff0000, v134
	v_pk_add_f32 v[164:165], v[140:141], v[164:165]
	v_cvt_pk_bf16_f32 v162, v164, v165
	v_lshlrev_b32_e32 v164, 16, v135
	v_and_b32_e32 v165, 0xffff0000, v135
	v_pk_add_f32 v[164:165], v[142:143], v[164:165]
	v_cvt_pk_bf16_f32 v163, v164, v165
	s_waitcnt vmcnt(3)
	s_nop 1
	v_mfma_f32_32x32x16_bf16 v[2:17], v[160:163], v[144:147], v[2:17]
	s_waitcnt vmcnt(2)
	v_mfma_f32_32x32x16_bf16 v[18:33], v[160:163], v[148:151], v[18:33]
	s_waitcnt vmcnt(1)
	v_mfma_f32_32x32x16_bf16 v[34:49], v[160:163], v[152:155], v[34:49]
	s_waitcnt vmcnt(0)
	v_mfma_f32_32x32x16_bf16 v[50:65], v[160:163], v[156:159], v[50:65]
	s_mov_b64 s[48:49], 0x200
	v_lshl_add_u64 v[72:73], v[72:73], 0, s[10:11]
	v_lshl_add_u64 v[76:77], v[76:77], 0, s[48:49]
	s_add_u32 s42, s42, 0x200
	s_addc_u32 s43, s43, 0
	s_cmpk_eq_i32 s42, 0x800
	s_cbranch_scc0 .LBB0_541
; DI int crow(int i, int h) { return (i & 3) + 8 * (i >> 2) + 4 * h; }
; DI void cmp_tile(const Params& p, int l, int tile, char* smem) {
;     ...
;   __syncthreads();
; #pragma unroll
;   for (int nf = 0; nf < 4; ++nf)
; #pragma unroll
;     for (int i = 0; i < 16; ++i) part[w][crow(i, half)][nf * 32 + r] = acc[nf][i];
;   __syncthreads();
;   float hv[16];
; #pragma unroll
;   for (int e = 0; e < 16; ++e) {
;     const int idx = tid + 256 * e, row = idx >> 7, col = idx & 127;
;     hv[e] = gelu_tanh((part[0][row][col] + part[1][row][col]) + (part[2][row][col] + part[3][row][col]));
;   }
	v_bfe_u32 v66, v86, 5, 1
	v_lshlrev_b32_e32 v0, 14, v87
	v_lshlrev_b32_e32 v68, 11, v66
	v_lshlrev_b32_e32 v67, 2, v88
	v_or3_b32 v0, v0, v68, v67
	s_barrier
	s_nop 0
	ds_write2_b32 v0, v2, v18 offset1:32
	ds_write2_b32 v0, v3, v19 offset0:128 offset1:160
	v_add_u32_e32 v2, 0x400, v0
	ds_write2_b32 v2, v4, v20 offset1:32
	ds_write2_b32 v2, v5, v21 offset0:128 offset1:160
	v_add_u32_e32 v3, 0x1000, v0
	v_add_u32_e32 v4, 0x1400, v0
	ds_write2_b32 v3, v6, v22 offset1:32
	ds_write2_b32 v3, v7, v23 offset0:128 offset1:160
	ds_write2_b32 v4, v8, v24 offset1:32
	ds_write2_b32 v4, v9, v25 offset0:128 offset1:160
	v_add_u32_e32 v5, 0x2000, v0
	v_add_u32_e32 v6, 0x2400, v0
	v_add_u32_e32 v7, 0x3000, v0
	v_add_u32_e32 v8, 0x3400, v0
	ds_write2_b32 v5, v10, v26 offset1:32
	ds_write2_b32 v5, v11, v27 offset0:128 offset1:160
	ds_write2_b32 v6, v12, v28 offset1:32
	ds_write2_b32 v6, v13, v29 offset0:128 offset1:160
	ds_write2_b32 v7, v14, v30 offset1:32
	ds_write2_b32 v7, v15, v31 offset0:128 offset1:160
	ds_write2_b32 v8, v16, v32 offset1:32
	ds_write2_b32 v8, v17, v33 offset0:128 offset1:160
	ds_write2_b32 v0, v34, v50 offset0:64 offset1:96
	ds_write2_b32 v0, v35, v51 offset0:192 offset1:224
	ds_write2_b32 v2, v36, v52 offset0:64 offset1:96
	ds_write2_b32 v2, v37, v53 offset0:192 offset1:224
	ds_write2_b32 v3, v38, v54 offset0:64 offset1:96
	ds_write2_b32 v3, v39, v55 offset0:192 offset1:224
	ds_write2_b32 v4, v40, v56 offset0:64 offset1:96
	ds_write2_b32 v4, v41, v57 offset0:192 offset1:224
	ds_write2_b32 v5, v42, v58 offset0:64 offset1:96
	ds_write2_b32 v5, v43, v59 offset0:192 offset1:224
	ds_write2_b32 v6, v44, v60 offset0:64 offset1:96
	ds_write2_b32 v6, v45, v61 offset0:192 offset1:224
	ds_write2_b32 v7, v46, v62 offset0:64 offset1:96
	ds_write2_b32 v7, v47, v63 offset0:192 offset1:224
	ds_write2_b32 v8, v48, v64 offset0:64 offset1:96
	ds_write2_b32 v8, v49, v65 offset0:192 offset1:224
	v_and_b32_e32 v2, 0x7f, v86
	v_lshlrev_b32_e32 v4, 2, v2
	v_ashrrev_i32_e32 v0, 7, v86
	v_lshl_or_b32 v3, v0, 9, v4
	s_waitcnt lgkmcnt(0)
	s_barrier
	ds_read2st64_b32 v[6:7], v3 offset1:64
	ds_read2st64_b32 v[8:9], v3 offset0:128 offset1:192
	v_lshlrev_b32_e32 v2, 1, v2
	s_movk_i32 s9, 0x110
	s_movk_i32 s51, 0x110
	s_waitcnt lgkmcnt(1)
	v_add_f32_e32 v3, v6, v7
	s_waitcnt lgkmcnt(0)
	v_add_f32_e32 v5, v8, v9
	v_add_f32_e32 v5, v3, v5
	v_mul_f32_e32 v3, 0x3d372713, v5
	v_mul_f32_e32 v3, v5, v3
	v_fma_f32 v3, v5, v3, v5
	v_mul_f32_e32 v3, 0x3f4c422a, v3
	v_add_f32_e32 v3, v3, v3
	v_mul_f32_e32 v3, 0x3fb8aa3b, v3
	v_exp_f32_e32 v3, v3
	v_mul_f32_e32 v5, 0.5, v5
	v_add_f32_e32 v10, 1.0, v3
	v_div_scale_f32 v11, s[42:43], v10, v10, 2.0
	v_rcp_f32_e32 v12, v11
	v_div_scale_f32 v13, vcc, 2.0, v10, 2.0
	v_fma_f32 v3, -v11, v12, 1.0
	v_fmac_f32_e32 v12, v3, v12
	v_add_u32_e32 v3, 0x100, v86
	v_ashrrev_i32_e32 v3, 7, v3
	v_lshl_or_b32 v8, v3, 9, v4
	ds_read2st64_b32 v[6:7], v8 offset1:64
	ds_read2st64_b32 v[8:9], v8 offset0:128 offset1:192
	v_mul_f32_e32 v14, v13, v12
	v_fma_f32 v15, -v11, v14, v13
	v_fmac_f32_e32 v14, v15, v12
	s_waitcnt lgkmcnt(1)
	v_add_f32_e32 v6, v6, v7
	s_waitcnt lgkmcnt(0)
	v_add_f32_e32 v7, v8, v9
	v_add_f32_e32 v7, v6, v7
	v_mul_f32_e32 v6, 0x3d372713, v7
	v_mul_f32_e32 v6, v7, v6
	v_fma_f32 v6, v7, v6, v7
	v_mul_f32_e32 v6, 0x3f4c422a, v6
	v_add_f32_e32 v6, v6, v6
	v_mul_f32_e32 v6, 0x3fb8aa3b, v6
	v_exp_f32_e32 v6, v6
	v_fma_f32 v11, -v11, v14, v13
	v_div_fmas_f32 v8, v11, v12, v14
	v_div_fixup_f32 v8, v8, v10, 2.0
	v_add_f32_e32 v12, 1.0, v6
	v_div_scale_f32 v13, s[42:43], v12, v12, 2.0
	v_rcp_f32_e32 v14, v13
	v_sub_f32_e32 v8, 1.0, v8
	v_add_f32_e32 v6, 1.0, v8
	v_mul_f32_e32 v5, v5, v6
	v_fma_f32 v6, -v13, v14, 1.0
	v_fmac_f32_e32 v14, v6, v14
	v_add_u32_e32 v6, 0x200, v86
	v_ashrrev_i32_e32 v6, 7, v6
	v_lshl_or_b32 v10, v6, 9, v4
	ds_read2st64_b32 v[8:9], v10 offset1:64
	ds_read2st64_b32 v[10:11], v10 offset0:128 offset1:192
	v_div_scale_f32 v15, vcc, 2.0, v12, 2.0
	v_mul_f32_e32 v16, v15, v14
	s_waitcnt lgkmcnt(1)
	v_add_f32_e32 v8, v8, v9
	s_waitcnt lgkmcnt(0)
	v_add_f32_e32 v9, v10, v11
	v_add_f32_e32 v9, v8, v9
	v_mul_f32_e32 v8, 0x3d372713, v9
	v_mul_f32_e32 v8, v9, v8
	v_fma_f32 v8, v9, v8, v9
	v_mul_f32_e32 v8, 0x3f4c422a, v8
	v_add_f32_e32 v8, v8, v8
	v_mul_f32_e32 v8, 0x3fb8aa3b, v8
	v_exp_f32_e32 v8, v8
	v_fma_f32 v17, -v13, v16, v15
	v_fmac_f32_e32 v16, v17, v14
	v_fma_f32 v13, -v13, v16, v15
	v_div_fmas_f32 v10, v13, v14, v16
	v_add_f32_e32 v14, 1.0, v8
	v_div_scale_f32 v15, s[42:43], v14, v14, 2.0
	v_rcp_f32_e32 v16, v15
	v_div_fixup_f32 v10, v10, v12, 2.0
	v_sub_f32_e32 v10, 1.0, v10
	v_mul_f32_e32 v7, 0.5, v7
	v_add_f32_e32 v8, 1.0, v10
	v_mul_f32_e32 v7, v7, v8
	v_fma_f32 v8, -v15, v16, 1.0
	v_fmac_f32_e32 v16, v8, v16
	v_add_u32_e32 v8, 0x300, v86
	v_ashrrev_i32_e32 v8, 7, v8
	v_lshl_or_b32 v12, v8, 9, v4
	ds_read2st64_b32 v[10:11], v12 offset1:64
	ds_read2st64_b32 v[12:13], v12 offset0:128 offset1:192
	v_div_scale_f32 v17, vcc, 2.0, v14, 2.0
	v_mul_f32_e32 v18, v17, v16
	s_waitcnt lgkmcnt(1)
	v_add_f32_e32 v10, v10, v11
	s_waitcnt lgkmcnt(0)
	v_add_f32_e32 v11, v12, v13
	v_add_f32_e32 v11, v10, v11
	v_mul_f32_e32 v10, 0x3d372713, v11
	v_mul_f32_e32 v10, v11, v10
	v_fma_f32 v10, v11, v10, v11
	v_mul_f32_e32 v10, 0x3f4c422a, v10
	v_add_f32_e32 v10, v10, v10
	v_mul_f32_e32 v10, 0x3fb8aa3b, v10
	v_exp_f32_e32 v10, v10
	v_fma_f32 v19, -v15, v18, v17
	v_fmac_f32_e32 v18, v19, v16
	v_fma_f32 v15, -v15, v18, v17
	v_div_fmas_f32 v12, v15, v16, v18
	v_add_f32_e32 v16, 1.0, v10
	v_div_scale_f32 v17, s[42:43], v16, v16, 2.0
	v_rcp_f32_e32 v18, v17
	v_div_fixup_f32 v12, v12, v14, 2.0
	v_sub_f32_e32 v12, 1.0, v12
	v_mul_f32_e32 v9, 0.5, v9
	v_add_f32_e32 v10, 1.0, v12
	v_mul_f32_e32 v9, v9, v10
	v_fma_f32 v10, -v17, v18, 1.0
	v_fmac_f32_e32 v18, v10, v18
	v_add_u32_e32 v10, 0x400, v86
	v_ashrrev_i32_e32 v10, 7, v10
	v_lshl_or_b32 v14, v10, 9, v4
	ds_read2st64_b32 v[12:13], v14 offset1:64
	ds_read2st64_b32 v[14:15], v14 offset0:128 offset1:192
	v_div_scale_f32 v19, vcc, 2.0, v16, 2.0
	v_mul_f32_e32 v20, v19, v18
	s_waitcnt lgkmcnt(1)
; DI float gelu_tanh(float x) {
;   const float u = 0.7978845608028654f * (x + 0.044715f * x * x * x);
;   const float e = __expf(2.f * u);
;   const float th = 1.f - 2.f / (e + 1.f);
;   return 0.5f * x * (1.f + th);
; }
; DI void cmp_tile(const Params& p, int l, int tile, char* smem) {
;     ...
;   float hv[16];
; #pragma unroll
;   for (int e = 0; e < 16; ++e) {
;     const int idx = tid + 256 * e, row = idx >> 7, col = idx & 127;
;     hv[e] = gelu_tanh((part[0][row][col] + part[1][row][col]) + (part[2][row][col] + part[3][row][col]));
;   }
	v_add_f32_e32 v12, v12, v13
	s_waitcnt lgkmcnt(0)
	v_add_f32_e32 v13, v14, v15
	v_add_f32_e32 v13, v12, v13
	v_mul_f32_e32 v12, 0x3d372713, v13
	v_mul_f32_e32 v12, v13, v12
	v_fma_f32 v12, v13, v12, v13
	v_mul_f32_e32 v12, 0x3f4c422a, v12
	v_add_f32_e32 v12, v12, v12
	v_mul_f32_e32 v12, 0x3fb8aa3b, v12
	v_exp_f32_e32 v12, v12
	v_fma_f32 v21, -v17, v20, v19
	v_fmac_f32_e32 v20, v21, v18
	v_fma_f32 v17, -v17, v20, v19
	v_div_fmas_f32 v14, v17, v18, v20
	v_add_f32_e32 v18, 1.0, v12
	v_div_scale_f32 v19, s[42:43], v18, v18, 2.0
	v_rcp_f32_e32 v20, v19
	v_div_fixup_f32 v14, v14, v16, 2.0
	v_sub_f32_e32 v14, 1.0, v14
	v_mul_f32_e32 v11, 0.5, v11
	v_add_f32_e32 v12, 1.0, v14
	v_mul_f32_e32 v11, v11, v12
	v_fma_f32 v12, -v19, v20, 1.0
	v_fmac_f32_e32 v20, v12, v20
	v_add_u32_e32 v12, 0x500, v86
	v_ashrrev_i32_e32 v12, 7, v12
	v_lshl_or_b32 v16, v12, 9, v4
	ds_read2st64_b32 v[14:15], v16 offset1:64
	ds_read2st64_b32 v[16:17], v16 offset0:128 offset1:192
	v_div_scale_f32 v21, vcc, 2.0, v18, 2.0
	v_mul_f32_e32 v22, v21, v20
	v_fma_f32 v23, -v19, v22, v21
	v_fmac_f32_e32 v22, v23, v20
	s_waitcnt lgkmcnt(1)
	v_add_f32_e32 v14, v14, v15
	s_waitcnt lgkmcnt(0)
	v_add_f32_e32 v15, v16, v17
	v_fma_f32 v19, -v19, v22, v21
	v_add_f32_e32 v21, v14, v15
	v_mul_f32_e32 v14, 0x3d372713, v21
	v_mul_f32_e32 v14, v21, v14
	v_fma_f32 v14, v21, v14, v21
	v_mul_f32_e32 v14, 0x3f4c422a, v14
	v_add_f32_e32 v14, v14, v14
	v_mul_f32_e32 v14, 0x3fb8aa3b, v14
	v_exp_f32_e32 v14, v14
	v_div_fmas_f32 v15, v19, v20, v22
	v_div_fixup_f32 v15, v15, v18, 2.0
	v_sub_f32_e32 v15, 1.0, v15
	v_add_f32_e32 v18, 1.0, v14
	v_div_scale_f32 v19, s[42:43], v18, v18, 2.0
	v_rcp_f32_e32 v20, v19
	v_mul_f32_e32 v13, 0.5, v13
	v_add_f32_e32 v14, 1.0, v15
	v_mul_f32_e32 v13, v13, v14
	v_fma_f32 v14, -v19, v20, 1.0
	v_fmac_f32_e32 v20, v14, v20
	v_add_u32_e32 v14, 0x600, v86
	v_ashrrev_i32_e32 v24, 7, v14
	v_lshl_or_b32 v16, v24, 9, v4
	ds_read2st64_b32 v[14:15], v16 offset1:64
	ds_read2st64_b32 v[16:17], v16 offset0:128 offset1:192
	v_div_scale_f32 v22, vcc, 2.0, v18, 2.0
	v_mul_f32_e32 v23, v22, v20
	v_fma_f32 v25, -v19, v23, v22
	v_fmac_f32_e32 v23, v25, v20
	s_waitcnt lgkmcnt(1)
	v_add_f32_e32 v14, v14, v15
	s_waitcnt lgkmcnt(0)
	v_add_f32_e32 v15, v16, v17
	v_fma_f32 v19, -v19, v23, v22
	v_add_f32_e32 v22, v14, v15
	v_mul_f32_e32 v14, 0x3d372713, v22
	v_mul_f32_e32 v14, v22, v14
	v_fma_f32 v14, v22, v14, v22
	v_mul_f32_e32 v14, 0x3f4c422a, v14
	v_add_f32_e32 v14, v14, v14
	v_mul_f32_e32 v14, 0x3fb8aa3b, v14
	v_exp_f32_e32 v14, v14
	v_div_fmas_f32 v15, v19, v20, v23
	v_div_fixup_f32 v15, v15, v18, 2.0
	v_sub_f32_e32 v15, 1.0, v15
	v_add_f32_e32 v18, 1.0, v14
	v_div_scale_f32 v19, s[42:43], v18, v18, 2.0
	v_rcp_f32_e32 v20, v19
	v_mul_f32_e32 v14, 0.5, v21
	v_add_f32_e32 v15, 1.0, v15
	v_mul_f32_e32 v21, v14, v15
	v_fma_f32 v14, -v19, v20, 1.0
	v_fmac_f32_e32 v20, v14, v20
	v_add_u32_e32 v14, 0x700, v86
	v_ashrrev_i32_e32 v26, 7, v14
	v_lshl_or_b32 v16, v26, 9, v4
	ds_read2st64_b32 v[14:15], v16 offset1:64
	ds_read2st64_b32 v[16:17], v16 offset0:128 offset1:192
	v_div_scale_f32 v23, vcc, 2.0, v18, 2.0
	v_mul_f32_e32 v25, v23, v20
	v_fma_f32 v27, -v19, v25, v23
	v_fmac_f32_e32 v25, v27, v20
	s_waitcnt lgkmcnt(1)
	v_add_f32_e32 v14, v14, v15
	s_waitcnt lgkmcnt(0)
	v_add_f32_e32 v15, v16, v17
	v_fma_f32 v19, -v19, v25, v23
	v_add_f32_e32 v23, v14, v15
	v_mul_f32_e32 v14, 0x3d372713, v23
	v_mul_f32_e32 v14, v23, v14
	v_fma_f32 v14, v23, v14, v23
	v_mul_f32_e32 v14, 0x3f4c422a, v14
	v_add_f32_e32 v14, v14, v14
	v_mul_f32_e32 v14, 0x3fb8aa3b, v14
	v_exp_f32_e32 v14, v14
	v_div_fmas_f32 v15, v19, v20, v25
	v_div_fixup_f32 v15, v15, v18, 2.0
	v_sub_f32_e32 v15, 1.0, v15
	v_add_f32_e32 v18, 1.0, v14
	v_div_scale_f32 v19, s[42:43], v18, v18, 2.0
	v_rcp_f32_e32 v20, v19
	v_mul_f32_e32 v14, 0.5, v22
	v_add_f32_e32 v15, 1.0, v15
	v_mul_f32_e32 v22, v14, v15
	v_fma_f32 v14, -v19, v20, 1.0
	v_fmac_f32_e32 v20, v14, v20
	v_add_u32_e32 v14, 0x800, v86
	v_ashrrev_i32_e32 v28, 7, v14
	v_lshl_or_b32 v16, v28, 9, v4
	ds_read2st64_b32 v[14:15], v16 offset1:64
	ds_read2st64_b32 v[16:17], v16 offset0:128 offset1:192
	v_div_scale_f32 v25, vcc, 2.0, v18, 2.0
	v_mul_f32_e32 v27, v25, v20
	v_fma_f32 v29, -v19, v27, v25
	v_fmac_f32_e32 v27, v29, v20
	s_waitcnt lgkmcnt(1)
	v_add_f32_e32 v14, v14, v15
	s_waitcnt lgkmcnt(0)
	v_add_f32_e32 v15, v16, v17
	v_fma_f32 v19, -v19, v27, v25
	v_add_f32_e32 v25, v14, v15
	v_mul_f32_e32 v14, 0x3d372713, v25
	v_mul_f32_e32 v14, v25, v14
	v_fma_f32 v14, v25, v14, v25
	v_mul_f32_e32 v14, 0x3f4c422a, v14
	v_add_f32_e32 v14, v14, v14
	v_mul_f32_e32 v14, 0x3fb8aa3b, v14
	v_exp_f32_e32 v14, v14
	v_div_fmas_f32 v15, v19, v20, v27
	v_div_fixup_f32 v15, v15, v18, 2.0
	v_sub_f32_e32 v15, 1.0, v15
	v_add_f32_e32 v18, 1.0, v14
	v_div_scale_f32 v19, s[42:43], v18, v18, 2.0
	v_rcp_f32_e32 v20, v19
	v_mul_f32_e32 v14, 0.5, v23
	v_add_f32_e32 v15, 1.0, v15
	v_mul_f32_e32 v23, v14, v15
	v_fma_f32 v14, -v19, v20, 1.0
	v_fmac_f32_e32 v20, v14, v20
	v_add_u32_e32 v14, 0x900, v86
	v_ashrrev_i32_e32 v30, 7, v14
	v_lshl_or_b32 v16, v30, 9, v4
	ds_read2st64_b32 v[14:15], v16 offset1:64
	ds_read2st64_b32 v[16:17], v16 offset0:128 offset1:192
	v_div_scale_f32 v27, vcc, 2.0, v18, 2.0
	v_mul_f32_e32 v29, v27, v20
	v_fma_f32 v31, -v19, v29, v27
	v_fmac_f32_e32 v29, v31, v20
	s_waitcnt lgkmcnt(1)
	v_add_f32_e32 v14, v14, v15
	s_waitcnt lgkmcnt(0)
; DI float gelu_tanh(float x) {
;   const float u = 0.7978845608028654f * (x + 0.044715f * x * x * x);
;   const float e = __expf(2.f * u);
;   const float th = 1.f - 2.f / (e + 1.f);
;   return 0.5f * x * (1.f + th);
; }
; DI void cmp_tile(const Params& p, int l, int tile, char* smem) {
;     ...
;   float hv[16];
; #pragma unroll
;   for (int e = 0; e < 16; ++e) {
;     const int idx = tid + 256 * e, row = idx >> 7, col = idx & 127;
;     hv[e] = gelu_tanh((part[0][row][col] + part[1][row][col]) + (part[2][row][col] + part[3][row][col]));
;   }
	v_add_f32_e32 v15, v16, v17
	v_fma_f32 v19, -v19, v29, v27
	v_add_f32_e32 v27, v14, v15
	v_mul_f32_e32 v14, 0x3d372713, v27
	v_mul_f32_e32 v14, v27, v14
	v_fma_f32 v14, v27, v14, v27
	v_mul_f32_e32 v14, 0x3f4c422a, v14
	v_add_f32_e32 v14, v14, v14
	v_mul_f32_e32 v14, 0x3fb8aa3b, v14
	v_exp_f32_e32 v14, v14
	v_div_fmas_f32 v15, v19, v20, v29
	v_div_fixup_f32 v15, v15, v18, 2.0
	v_sub_f32_e32 v15, 1.0, v15
	v_add_f32_e32 v18, 1.0, v14
	v_div_scale_f32 v19, s[42:43], v18, v18, 2.0
	v_rcp_f32_e32 v20, v19
	v_mul_f32_e32 v14, 0.5, v25
	v_add_f32_e32 v15, 1.0, v15
	v_mul_f32_e32 v25, v14, v15
	v_fma_f32 v14, -v19, v20, 1.0
	v_fmac_f32_e32 v20, v14, v20
	v_add_u32_e32 v14, 0xa00, v86
	v_ashrrev_i32_e32 v32, 7, v14
	v_lshl_or_b32 v16, v32, 9, v4
	ds_read2st64_b32 v[14:15], v16 offset1:64
	ds_read2st64_b32 v[16:17], v16 offset0:128 offset1:192
	v_div_scale_f32 v29, vcc, 2.0, v18, 2.0
	v_mul_f32_e32 v31, v29, v20
	v_fma_f32 v33, -v19, v31, v29
	v_fmac_f32_e32 v31, v33, v20
	s_waitcnt lgkmcnt(1)
	v_add_f32_e32 v14, v14, v15
	s_waitcnt lgkmcnt(0)
	v_add_f32_e32 v15, v16, v17
	v_fma_f32 v19, -v19, v31, v29
	v_add_f32_e32 v29, v14, v15
	v_mul_f32_e32 v14, 0x3d372713, v29
	v_mul_f32_e32 v14, v29, v14
	v_fma_f32 v14, v29, v14, v29
	v_mul_f32_e32 v14, 0x3f4c422a, v14
	v_add_f32_e32 v14, v14, v14
	v_mul_f32_e32 v14, 0x3fb8aa3b, v14
	v_exp_f32_e32 v14, v14
	v_div_fmas_f32 v15, v19, v20, v31
	v_div_fixup_f32 v15, v15, v18, 2.0
	v_sub_f32_e32 v15, 1.0, v15
	v_add_f32_e32 v18, 1.0, v14
	v_div_scale_f32 v19, s[42:43], v18, v18, 2.0
	v_rcp_f32_e32 v20, v19
	v_mul_f32_e32 v14, 0.5, v27
	v_add_f32_e32 v15, 1.0, v15
	v_mul_f32_e32 v27, v14, v15
	v_fma_f32 v14, -v19, v20, 1.0
	v_fmac_f32_e32 v20, v14, v20
	v_add_u32_e32 v14, 0xb00, v86
	v_ashrrev_i32_e32 v34, 7, v14
	v_lshl_or_b32 v16, v34, 9, v4
	ds_read2st64_b32 v[14:15], v16 offset1:64
	ds_read2st64_b32 v[16:17], v16 offset0:128 offset1:192
	v_div_scale_f32 v31, vcc, 2.0, v18, 2.0
	v_mul_f32_e32 v33, v31, v20
	v_fma_f32 v35, -v19, v33, v31
	v_fmac_f32_e32 v33, v35, v20
	s_waitcnt lgkmcnt(1)
	v_add_f32_e32 v14, v14, v15
	s_waitcnt lgkmcnt(0)
	v_add_f32_e32 v15, v16, v17
	v_fma_f32 v19, -v19, v33, v31
	v_add_f32_e32 v31, v14, v15
	v_mul_f32_e32 v14, 0x3d372713, v31
	v_mul_f32_e32 v14, v31, v14
	v_fma_f32 v14, v31, v14, v31
	v_mul_f32_e32 v14, 0x3f4c422a, v14
	v_add_f32_e32 v14, v14, v14
	v_mul_f32_e32 v14, 0x3fb8aa3b, v14
	v_exp_f32_e32 v14, v14
	v_div_fmas_f32 v15, v19, v20, v33
	v_div_fixup_f32 v15, v15, v18, 2.0
	v_sub_f32_e32 v15, 1.0, v15
	v_add_f32_e32 v18, 1.0, v14
	v_div_scale_f32 v19, s[42:43], v18, v18, 2.0
	v_rcp_f32_e32 v20, v19
	v_mul_f32_e32 v14, 0.5, v29
	v_add_f32_e32 v15, 1.0, v15
	v_mul_f32_e32 v29, v14, v15
	v_fma_f32 v14, -v19, v20, 1.0
	v_fmac_f32_e32 v20, v14, v20
	v_add_u32_e32 v14, 0xc00, v86
	v_ashrrev_i32_e32 v36, 7, v14
	v_lshl_or_b32 v16, v36, 9, v4
	ds_read2st64_b32 v[14:15], v16 offset1:64
	ds_read2st64_b32 v[16:17], v16 offset0:128 offset1:192
	v_div_scale_f32 v33, vcc, 2.0, v18, 2.0
	v_mul_f32_e32 v35, v33, v20
	v_fma_f32 v37, -v19, v35, v33
	v_fmac_f32_e32 v35, v37, v20
	s_waitcnt lgkmcnt(1)
	v_add_f32_e32 v14, v14, v15
	s_waitcnt lgkmcnt(0)
	v_add_f32_e32 v15, v16, v17
	v_fma_f32 v19, -v19, v35, v33
	v_add_f32_e32 v33, v14, v15
	v_mul_f32_e32 v14, 0x3d372713, v33
	v_mul_f32_e32 v14, v33, v14
	v_fma_f32 v14, v33, v14, v33
	v_mul_f32_e32 v14, 0x3f4c422a, v14
	v_add_f32_e32 v14, v14, v14
	v_mul_f32_e32 v14, 0x3fb8aa3b, v14
	v_exp_f32_e32 v14, v14
	v_div_fmas_f32 v15, v19, v20, v35
	v_div_fixup_f32 v15, v15, v18, 2.0
	v_sub_f32_e32 v15, 1.0, v15
	v_add_f32_e32 v18, 1.0, v14
	v_div_scale_f32 v19, s[42:43], v18, v18, 2.0
	v_rcp_f32_e32 v20, v19
	v_mul_f32_e32 v14, 0.5, v31
	v_add_f32_e32 v15, 1.0, v15
	v_mul_f32_e32 v31, v14, v15
	v_fma_f32 v14, -v19, v20, 1.0
	v_fmac_f32_e32 v20, v14, v20
	v_add_u32_e32 v14, 0xd00, v86
	v_ashrrev_i32_e32 v38, 7, v14
	v_lshl_or_b32 v16, v38, 9, v4
	ds_read2st64_b32 v[14:15], v16 offset1:64
	ds_read2st64_b32 v[16:17], v16 offset0:128 offset1:192
	v_div_scale_f32 v35, vcc, 2.0, v18, 2.0
	v_mul_f32_e32 v37, v35, v20
	v_fma_f32 v39, -v19, v37, v35
	v_fmac_f32_e32 v37, v39, v20
	s_waitcnt lgkmcnt(1)
	v_add_f32_e32 v14, v14, v15
	s_waitcnt lgkmcnt(0)
	v_add_f32_e32 v15, v16, v17
	v_fma_f32 v19, -v19, v37, v35
	v_add_f32_e32 v35, v14, v15
	v_mul_f32_e32 v14, 0x3d372713, v35
	v_mul_f32_e32 v14, v35, v14
	v_fma_f32 v14, v35, v14, v35
	v_mul_f32_e32 v14, 0x3f4c422a, v14
	v_add_f32_e32 v14, v14, v14
	v_mul_f32_e32 v14, 0x3fb8aa3b, v14
	v_exp_f32_e32 v14, v14
	v_div_fmas_f32 v15, v19, v20, v37
	v_div_fixup_f32 v15, v15, v18, 2.0
	v_sub_f32_e32 v15, 1.0, v15
	v_add_f32_e32 v18, 1.0, v14
	v_div_scale_f32 v19, s[42:43], v18, v18, 2.0
	v_rcp_f32_e32 v20, v19
	v_mul_f32_e32 v14, 0.5, v33
	v_add_f32_e32 v15, 1.0, v15
	v_mul_f32_e32 v33, v14, v15
	v_fma_f32 v14, -v19, v20, 1.0
	v_fmac_f32_e32 v20, v14, v20
	v_add_u32_e32 v14, 0xe00, v86
	v_ashrrev_i32_e32 v40, 7, v14
	v_lshl_or_b32 v16, v40, 9, v4
	ds_read2st64_b32 v[14:15], v16 offset1:64
	ds_read2st64_b32 v[16:17], v16 offset0:128 offset1:192
	v_div_scale_f32 v37, vcc, 2.0, v18, 2.0
	v_mul_f32_e32 v39, v37, v20
	v_fma_f32 v41, -v19, v39, v37
	v_fmac_f32_e32 v39, v41, v20
	s_waitcnt lgkmcnt(1)
	v_add_f32_e32 v14, v14, v15
	s_waitcnt lgkmcnt(0)
; #define MFMA32(a, b, c) __builtin_amdgcn_mfma_f32_32x32x16_bf16((a), (b), (c), 0, 0, 0)
; DI unsigned pk2(float a, float b) { f32x2 v = {a, b}; bf2_t r = __builtin_convertvector(v, bf2_t); return __builtin_bit_cast(unsigned, r); }
; DI int crow(int i, int h) { return (i & 3) + 8 * (i >> 2) + 4 * h; }
; DI void cmp_tile(const Params& p, int l, int tile, char* smem) {
;     ...
;   for (int e = 0; e < 16; ++e) {
;     const int idx = tid + 256 * e, row = idx >> 7, col = idx & 127;
;     hv[e] = gelu_tanh((part[0][row][col] + part[1][row][col]) + (part[2][row][col] + part[3][row][col]));
;   }
;   __syncthreads();
; #pragma unroll
;   for (int e = 0; e < 16; ++e) {
;     const int idx = tid + 256 * e, row = idx >> 7, col = idx & 127;
;     hid[row][col] = (bf16_t)(pk2(hv[e], 0.f) & 0xffff);
;   }
;   __syncthreads();
;   if (w < 2) {
;     f32x16 a2;
; #pragma unroll
;     for (int i = 0; i < 16; ++i) a2[i] = 0.f;
; #pragma unroll
;     for (int ks = 0; ks < 8; ++ks) {
;       const bf16x8 av = *(const bf16x8*)&hid[r][ks * 16 + half * 8];
;       const bf16x8 bv = *(const bf16x8*)(W2T + (size_t)(32 * w + r) * 128 + ks * 16 + half * 8);
;       a2 = MFMA32(av, bv, a2);
;     }
; #pragma unroll
;     for (int i = 0; i < 16; ++i) outf[crow(i, half)][32 * w + r] = a2[i];
	v_add_f32_e32 v15, v16, v17
	v_fma_f32 v19, -v19, v39, v37
	v_add_f32_e32 v37, v14, v15
	v_mul_f32_e32 v14, 0x3d372713, v37
	v_mul_f32_e32 v14, v37, v14
	v_fma_f32 v14, v37, v14, v37
	v_mul_f32_e32 v14, 0x3f4c422a, v14
	v_add_f32_e32 v14, v14, v14
	v_mul_f32_e32 v14, 0x3fb8aa3b, v14
	v_exp_f32_e32 v14, v14
	v_div_fmas_f32 v15, v19, v20, v39
	v_div_fixup_f32 v15, v15, v18, 2.0
	v_sub_f32_e32 v15, 1.0, v15
	v_add_f32_e32 v18, 1.0, v14
	v_div_scale_f32 v19, s[42:43], v18, v18, 2.0
	v_rcp_f32_e32 v20, v19
	v_mul_f32_e32 v14, 0.5, v35
	v_add_f32_e32 v15, 1.0, v15
	v_mul_f32_e32 v35, v14, v15
	v_fma_f32 v14, -v19, v20, 1.0
	v_fmac_f32_e32 v20, v14, v20
	v_add_u32_e32 v14, 0xf00, v86
	v_ashrrev_i32_e32 v42, 7, v14
	v_lshl_or_b32 v4, v42, 9, v4
	ds_read2st64_b32 v[14:15], v4 offset1:64
	ds_read2st64_b32 v[16:17], v4 offset0:128 offset1:192
	v_div_scale_f32 v39, vcc, 2.0, v18, 2.0
	v_mul_f32_e32 v41, v39, v20
	s_waitcnt lgkmcnt(1)
	v_add_f32_e32 v14, v14, v15
	s_waitcnt lgkmcnt(0)
	v_add_f32_e32 v15, v16, v17
	v_add_f32_e32 v14, v14, v15
	v_mul_f32_e32 v15, 0x3d372713, v14
	v_mul_f32_e32 v15, v14, v15
	v_fma_f32 v15, v14, v15, v14
	v_mul_f32_e32 v15, 0x3f4c422a, v15
	v_add_f32_e32 v15, v15, v15
	v_mul_f32_e32 v15, 0x3fb8aa3b, v15
	v_exp_f32_e32 v15, v15
	v_fma_f32 v4, -v19, v41, v39
	v_fmac_f32_e32 v41, v4, v20
	v_fma_f32 v4, -v19, v41, v39
	v_add_f32_e32 v15, 1.0, v15
	v_div_scale_f32 v16, s[42:43], v15, v15, 2.0
	v_div_fmas_f32 v4, v4, v20, v41
	v_rcp_f32_e32 v17, v16
	v_div_fixup_f32 v4, v4, v18, 2.0
	v_sub_f32_e32 v4, 1.0, v4
	v_mul_f32_e32 v18, 0.5, v37
	v_add_f32_e32 v4, 1.0, v4
	v_mul_f32_e32 v18, v18, v4
	v_fma_f32 v4, -v16, v17, 1.0
	v_fmac_f32_e32 v17, v4, v17
	v_div_scale_f32 v4, vcc, 2.0, v15, 2.0
	v_mul_f32_e32 v19, v4, v17
	v_fma_f32 v20, -v16, v19, v4
	v_fmac_f32_e32 v19, v20, v17
	v_fma_f32 v4, -v16, v19, v4
	v_div_fmas_f32 v4, v4, v17, v19
	v_div_fixup_f32 v4, v4, v15, 2.0
	v_sub_f32_e32 v4, 1.0, v4
	v_mul_f32_e32 v14, 0.5, v14
	v_add_f32_e32 v4, 1.0, v4
	v_mul_f32_e32 v14, v14, v4
	v_cvt_pk_bf16_f32 v15, v5, s0
	v_mad_u64_u32 v[4:5], s[42:43], v0, s9, v[2:3]
	s_barrier
	ds_write_b16 v4, v15
	v_cvt_pk_bf16_f32 v0, v7, s0
	v_mad_u64_u32 v[4:5], s[42:43], v3, s9, v[2:3]
	ds_write_b16 v4, v0
	v_cvt_pk_bf16_f32 v0, v9, s0
	v_mad_u64_u32 v[4:5], s[42:43], v6, s9, v[2:3]
	ds_write_b16 v4, v0
	v_cvt_pk_bf16_f32 v0, v11, s0
	v_mad_u64_u32 v[4:5], s[42:43], v8, s9, v[2:3]
	ds_write_b16 v4, v0
	v_cvt_pk_bf16_f32 v0, v13, s0
	v_mad_u64_u32 v[4:5], s[42:43], v10, s9, v[2:3]
	ds_write_b16 v4, v0
	v_cvt_pk_bf16_f32 v0, v21, s0
	v_mad_u64_u32 v[4:5], s[42:43], v12, s9, v[2:3]
	ds_write_b16 v4, v0
	v_cvt_pk_bf16_f32 v0, v22, s0
	v_mad_u64_u32 v[4:5], s[42:43], v24, s9, v[2:3]
	ds_write_b16 v4, v0
	v_cvt_pk_bf16_f32 v0, v23, s0
	v_mad_u64_u32 v[4:5], s[42:43], v26, s9, v[2:3]
	ds_write_b16 v4, v0
	v_cvt_pk_bf16_f32 v0, v25, s0
	v_mad_u64_u32 v[4:5], s[42:43], v28, s9, v[2:3]
	ds_write_b16 v4, v0
	v_cvt_pk_bf16_f32 v0, v27, s0
	v_mad_u64_u32 v[4:5], s[42:43], v30, s9, v[2:3]
	ds_write_b16 v4, v0
	v_cvt_pk_bf16_f32 v0, v29, s0
	v_mad_u64_u32 v[4:5], s[42:43], v32, s9, v[2:3]
	ds_write_b16 v4, v0
	v_cvt_pk_bf16_f32 v0, v31, s0
	v_mad_u64_u32 v[4:5], s[42:43], v34, s9, v[2:3]
	ds_write_b16 v4, v0
	v_cvt_pk_bf16_f32 v0, v33, s0
	v_mad_u64_u32 v[4:5], s[42:43], v36, s9, v[2:3]
	ds_write_b16 v4, v0
	v_cvt_pk_bf16_f32 v0, v35, s0
	v_mad_u64_u32 v[4:5], s[42:43], v38, s9, v[2:3]
	ds_write_b16 v4, v0
	v_cvt_pk_bf16_f32 v0, v18, s0
	v_mad_u64_u32 v[4:5], s[42:43], v40, s9, v[2:3]
	ds_write_b16 v4, v0
	v_cvt_pk_bf16_f32 v0, v14, s0
	v_mad_u64_u32 v[2:3], s[42:43], v42, s9, v[2:3]
	v_cmp_gt_i32_e32 vcc, 2, v87
	ds_write_b16 v2, v0
	s_waitcnt lgkmcnt(0)
	s_barrier
	s_and_saveexec_b64 s[42:43], vcc
	s_cbranch_execz .LBB0_544
	s_and_b64 s[36:37], s[36:37], exec
	s_mov_b32 s9, 0x1f40000
	s_cselect_b32 s9, s9, 0x1f44000
	v_lshl_or_b32 v2, v87, 5, v88
	s_add_u32 s36, s26, s9
	v_ashrrev_i32_e32 v3, 31, v2
	s_addc_u32 s37, s27, 0
	v_lshlrev_b64 v[2:3], 8, v[2:3]
	v_lshlrev_b32_e32 v0, 4, v66
	v_lshl_add_u64 v[2:3], s[36:37], 0, v[2:3]
	v_lshl_add_u64 v[26:27], v[2:3], 0, v[0:1]
	global_load_dwordx4 v[2:5], v[26:27], off
	v_mad_u32_u24 v28, v88, s51, v0
	ds_read_b128 v[6:9], v28
	ds_read_b128 v[18:21], v28 offset:32
	global_load_dwordx4 v[22:25], v[26:27], off offset:32
	v_mul_u32_u24_e32 v0, 0x440, v66
	s_waitcnt vmcnt(1) lgkmcnt(1)
	v_mfma_f32_32x32x16_bf16 v[2:17], v[6:9], v[2:5], 0
	s_waitcnt vmcnt(0) lgkmcnt(0)
	v_mfma_f32_32x32x16_bf16 v[2:17], v[18:21], v[22:25], v[2:17]
	global_load_dwordx4 v[22:25], v[26:27], off offset:64
	ds_read_b128 v[18:21], v28 offset:64
	s_waitcnt vmcnt(0) lgkmcnt(0)
	v_mfma_f32_32x32x16_bf16 v[2:17], v[18:21], v[22:25], v[2:17]
	global_load_dwordx4 v[22:25], v[26:27], off offset:96
	ds_read_b128 v[18:21], v28 offset:96
	s_waitcnt vmcnt(0) lgkmcnt(0)
	v_mfma_f32_32x32x16_bf16 v[2:17], v[18:21], v[22:25], v[2:17]
	global_load_dwordx4 v[22:25], v[26:27], off offset:128
	ds_read_b128 v[18:21], v28 offset:128
	s_waitcnt vmcnt(0) lgkmcnt(0)
	v_mfma_f32_32x32x16_bf16 v[2:17], v[18:21], v[22:25], v[2:17]
	global_load_dwordx4 v[22:25], v[26:27], off offset:160
	ds_read_b128 v[18:21], v28 offset:160
	s_waitcnt vmcnt(0) lgkmcnt(0)
	v_mfma_f32_32x32x16_bf16 v[2:17], v[18:21], v[22:25], v[2:17]
	global_load_dwordx4 v[22:25], v[26:27], off offset:192
	ds_read_b128 v[18:21], v28 offset:192
	s_waitcnt vmcnt(0) lgkmcnt(0)
	v_mfma_f32_32x32x16_bf16 v[2:17], v[18:21], v[22:25], v[2:17]
	global_load_dwordx4 v[22:25], v[26:27], off offset:224
	ds_read_b128 v[18:21], v28 offset:224
	s_waitcnt vmcnt(0) lgkmcnt(0)
	v_mfma_f32_32x32x16_bf16 v[2:17], v[18:21], v[22:25], v[2:17]
	v_lshlrev_b32_e32 v18, 7, v87
	v_add3_u32 v0, v0, v18, v67
	v_add_u32_e32 v18, 0x2000, v0
	s_nop 8
	ds_write2_b32 v18, v2, v3 offset0:128 offset1:196
	v_add_u32_e32 v2, 0x2400, v0
	ds_write2_b32 v2, v4, v5 offset0:8 offset1:76
	v_add_u32_e32 v2, 0x2800, v0
	ds_write2_b32 v2, v6, v7 offset0:160 offset1:228
	v_add_u32_e32 v2, 0x2c00, v0
	ds_write2_b32 v2, v8, v9 offset0:40 offset1:108
	v_add_u32_e32 v2, 0x3200, v0
	ds_write2_b32 v2, v10, v11 offset0:64 offset1:132
	v_add_u32_e32 v2, 0x3400, v0
	ds_write2_b32 v2, v12, v13 offset0:72 offset1:140
	v_add_u32_e32 v2, 0x3a00, v0
	v_add_u32_e32 v0, 0x3c00, v0
	ds_write2_b32 v2, v14, v15 offset0:96 offset1:164
	ds_write2_b32 v0, v16, v17 offset0:104 offset1:172
